# seam before W_out as panel dataflow: MIX stored write-through, every workgroup counts into the panels it produced, waits for its own panel's 36 contributions; grid round verified before FFN2 gate-up's
# speedup vs baseline: 1.0067x; 1.0010x over previous
; __device__ __forceinline__ unsigned pk2(float lo, float hi) { return pg8::cvt_pk_bf16(lo, hi); }
; template <int NR>
; __device__ __forceinline__ void conv_rows(const Args& a, int r0, int rstride, int lane) {
;     unsigned char* ws = a.ws; const int c0 = 8 * lane;
;     const bf16* BCp = (const bf16*)(ws + WS_BC); const bf16* CUp = (const bf16*)(ws + WS_CU);
;     v4u bq[NR], u0[NR], u1[NR], u2[NR];
; #pragma unroll
;     for (int i = 0; i < NR; ++i) { const int row = r0 + i * rstride, t = row & (SEQ - 1);
;         bq[i] = *(const v4u*)(BCp + (size_t)row * 512 + c0); u0[i] = *(const v4u*)(CUp + (size_t)row * 512 + c0);
;         u1[i] = (v4u){0, 0, 0, 0}; u2[i] = (v4u){0, 0, 0, 0};
;         if (t >= 1) u1[i] = *(const v4u*)(CUp + (size_t)(row - 1) * 512 + c0);
;         if (t >= 2) u2[i] = *(const v4u*)(CUp + (size_t)(row - 2) * 512 + c0); }
;     const float* cw = a.in[I_CONVW] + c0; const float* gn = a.in[I_CONVN] + c0;
;     const f32x4 w0a = *(const f32x4*)(cw), w0b = *(const f32x4*)(cw + 4), w1a = *(const f32x4*)(cw + 512), w1b = *(const f32x4*)(cw + 516), w2a = *(const f32x4*)(cw + 1024), w2b = *(const f32x4*)(cw + 1028);
;     const f32x4 ga = *(const f32x4*)(gn), gb = *(const f32x4*)(gn + 4);
; #pragma unroll
;     for (int i = 0; i < NR; ++i) { const int row = r0 + i * rstride; float y[8]; float s = 0.f;
; #pragma unroll
;         for (int j = 0; j < 8; ++j) { const int sh = (j & 1) * 16; const unsigned ub = bq[i][j >> 1], x0 = u0[i][j >> 1], x1 = u1[i][j >> 1], x2 = u2[i][j >> 1];
;             const float B = __uint_as_float(((ub >> sh) & 0xffffu) << 16), c_0 = __uint_as_float(((x0 >> sh) & 0xffffu) << 16), c_1 = __uint_as_float(((x1 >> sh) & 0xffffu) << 16), c_2 = __uint_as_float(((x2 >> sh) & 0xffffu) << 16);
;             const float k0 = j < 4 ? w0a[j & 3] : w0b[j & 3], k1 = j < 4 ? w1a[j & 3] : w1b[j & 3], k2 = j < 4 ? w2a[j & 3] : w2b[j & 3];
;             y[j] = B * (k0 * c_2 + k1 * c_1 + k2 * c_0); s += y[j] * y[j]; }
;         s = wave_sum(s); const float rs = rsqrtf(s * (1.f / 512.f) + EPS);
;         v4u o; o.x = pk2(y[0] * rs * ga[0], y[1] * rs * ga[1]); o.y = pk2(y[2] * rs * ga[2], y[3] * rs * ga[3]); o.z = pk2(y[4] * rs * gb[0], y[5] * rs * gb[1]); o.w = pk2(y[6] * rs * gb[2], y[7] * rs * gb[3]);
;         pg8::st_wt16((bf16*)(ws + WS_MIX) + (size_t)row * 1024 + 512 + c0, o); }
.LBB0_747:
	global_load_dwordx4 v[20:23], v[10:11], off
	global_load_dwordx4 v[24:27], v[100:101], off offset:2064
	global_load_dwordx4 v[28:31], v[100:101], off offset:2048
	v_add_co_u32_e32 v60, vcc, 0x1000000, v10
	global_load_dwordx4 v[32:35], v[100:101], off
	global_load_dwordx4 v[36:39], v[100:101], off offset:16
	v_addc_co_u32_e32 v61, vcc, 0, v11, vcc
	global_load_dwordx4 v[40:43], v[60:61], off
	global_load_dwordx4 v[44:47], v[104:105], off offset:16
	global_load_dwordx4 v[48:51], v[104:105], off
	global_load_dwordx4 v[52:55], v[102:103], off offset:16
	global_load_dwordx4 v[56:59], v[102:103], off
	s_waitcnt vmcnt(10)
	v_lshlrev_b32_e32 v60, 16, v7
	v_and_b32_e32 v61, 0xffff0000, v7
	v_lshlrev_b32_e32 v62, 16, v3
	v_and_b32_e32 v63, 0xffff0000, v3
	v_lshlrev_b32_e32 v64, 16, v6
	v_and_b32_e32 v65, 0xffff0000, v6
	v_lshlrev_b32_e32 v6, 16, v2
	v_and_b32_e32 v7, 0xffff0000, v2
	v_lshlrev_b32_e32 v2, 16, v5
	v_and_b32_e32 v3, 0xffff0000, v5
	v_lshlrev_b32_e32 v66, 16, v1
	v_and_b32_e32 v67, 0xffff0000, v1
	v_lshlrev_b32_e32 v68, 16, v4
	v_and_b32_e32 v69, 0xffff0000, v4
	v_lshlrev_b32_e32 v4, 16, v0
	v_and_b32_e32 v5, 0xffff0000, v0
	s_add_i32 s11, s11, s58
	s_cmpk_lt_i32 s11, 0x4000
	v_lshl_add_u64 v[10:11], v[10:11], 0, s[8:9]
	s_waitcnt vmcnt(9)
	v_lshlrev_b32_e32 v0, 16, v23
	v_and_b32_e32 v1, 0xffff0000, v23
	s_waitcnt vmcnt(8)
	v_pk_mul_f32 v[6:7], v[24:25], v[6:7]
	v_lshlrev_b32_e32 v24, 16, v22
	v_and_b32_e32 v25, 0xffff0000, v22
	s_waitcnt vmcnt(7)
	v_pk_mul_f32 v[22:23], v[30:31], v[66:67]
	v_pk_mul_f32 v[4:5], v[28:29], v[4:5]
	s_waitcnt vmcnt(6)
	v_pk_fma_f32 v[2:3], v[34:35], v[2:3], v[22:23]
	v_pk_fma_f32 v[4:5], v[32:33], v[68:69], v[4:5]
	s_waitcnt vmcnt(4)
	v_lshlrev_b32_e32 v34, 16, v40
	v_and_b32_e32 v35, 0xffff0000, v40
	v_pk_mul_f32 v[26:27], v[26:27], v[62:63]
	v_lshlrev_b32_e32 v28, 16, v20
	v_and_b32_e32 v29, 0xffff0000, v20
	v_lshlrev_b32_e32 v32, 16, v41
	v_and_b32_e32 v33, 0xffff0000, v41
	s_waitcnt vmcnt(2)
	v_pk_fma_f32 v[4:5], v[48:49], v[34:35], v[4:5]
	v_lshlrev_b32_e32 v30, 16, v21
	v_and_b32_e32 v31, 0xffff0000, v21
	v_pk_fma_f32 v[20:21], v[38:39], v[60:61], v[26:27]
	v_pk_fma_f32 v[6:7], v[36:37], v[64:65], v[6:7]
	v_lshlrev_b32_e32 v26, 16, v42
	v_and_b32_e32 v27, 0xffff0000, v42
	v_pk_fma_f32 v[2:3], v[50:51], v[32:33], v[2:3]
	v_pk_mul_f32 v[4:5], v[4:5], v[28:29]
	v_pk_fma_f32 v[6:7], v[44:45], v[26:27], v[6:7]
	v_pk_mul_f32 v[2:3], v[2:3], v[30:31]
	v_pk_mul_f32 v[26:27], v[4:5], v[4:5]
	v_pk_mul_f32 v[6:7], v[6:7], v[24:25]
	v_pk_mul_f32 v[24:25], v[2:3], v[2:3]
	v_add_f32_e32 v19, v26, v27
	v_lshlrev_b32_e32 v22, 16, v43
	v_and_b32_e32 v23, 0xffff0000, v43
	v_add_f32_e32 v19, v24, v19
	v_pk_fma_f32 v[20:21], v[46:47], v[22:23], v[20:21]
	v_pk_mul_f32 v[22:23], v[6:7], v[6:7]
	v_add_f32_e32 v19, v25, v19
	v_pk_mul_f32 v[0:1], v[20:21], v[0:1]
	v_add_f32_e32 v19, v22, v19
	v_pk_mul_f32 v[20:21], v[0:1], v[0:1]
	v_add_f32_e32 v19, v23, v19
	v_add_f32_e32 v19, v20, v19
	v_add_f32_e32 v19, v21, v19
	ds_bpermute_b32 v20, v17, v19
	s_waitcnt lgkmcnt(0)
	v_add_f32_e32 v19, v19, v20
	ds_bpermute_b32 v20, v16, v19
	s_waitcnt lgkmcnt(0)
	v_add_f32_e32 v19, v19, v20
	ds_bpermute_b32 v20, v15, v19
	s_waitcnt lgkmcnt(0)
	v_add_f32_e32 v19, v19, v20
	ds_bpermute_b32 v20, v14, v19
	s_waitcnt lgkmcnt(0)
	v_add_f32_e32 v19, v19, v20
	ds_bpermute_b32 v20, v13, v19
	s_waitcnt lgkmcnt(0)
	v_add_f32_e32 v19, v19, v20
	ds_bpermute_b32 v20, v12, v19
	s_waitcnt lgkmcnt(0)
	v_add_f32_e32 v19, v19, v20
	v_fmamk_f32 v19, v19, 0x3b000000, v18
	v_mul_f32_e32 v20, 0x4b800000, v19
	v_cmp_gt_f32_e32 vcc, s10, v19
	s_nop 1
	v_cndmask_b32_e32 v19, v19, v20, vcc
	v_rsq_f32_e32 v19, v19
	s_nop 0
	v_mul_f32_e32 v20, 0x45800000, v19
	v_cndmask_b32_e32 v20, v19, v20, vcc
	v_pk_mul_f32 v[4:5], v[4:5], v[20:21] op_sel_hi:[1,0]
	v_pk_mul_f32 v[2:3], v[2:3], v[20:21] op_sel_hi:[1,0]
	v_pk_mul_f32 v[6:7], v[6:7], v[20:21] op_sel_hi:[1,0]
	v_pk_mul_f32 v[0:1], v[0:1], v[20:21] op_sel_hi:[1,0]
	s_waitcnt vmcnt(0)
	v_pk_mul_f32 v[4:5], v[56:57], v[4:5]
	v_pk_mul_f32 v[2:3], v[58:59], v[2:3]
	v_pk_mul_f32 v[6:7], v[52:53], v[6:7]
	v_pk_mul_f32 v[20:21], v[54:55], v[0:1]
	v_cvt_pk_bf16_f32 v0, v4, v5
	v_cvt_pk_bf16_f32 v1, v2, v3
	v_cvt_pk_bf16_f32 v2, v6, v7
	v_cvt_pk_bf16_f32 v3, v20, v21
	global_store_dwordx4 v[8:9], v[0:3], off sc1
	v_lshl_add_u64 v[8:9], v[8:9], 0, s[6:7]
	s_cbranch_scc0 .LBB0_753

; template <int NR>
; __device__ __forceinline__ void conv_rows(const Args& a, int r0, int rstride, int lane) {
;     ...
;     for (int i = 0; i < NR; ++i) { const int row = r0 + i * rstride, t = row & (SEQ - 1);
;         bq[i] = *(const v4u*)(BCp + (size_t)row * 512 + c0); u0[i] = *(const v4u*)(CUp + (size_t)row * 512 + c0);
;         u1[i] = (v4u){0, 0, 0, 0}; u2[i] = (v4u){0, 0, 0, 0};
;         if (t >= 1) u1[i] = *(const v4u*)(CUp + (size_t)(row - 1) * 512 + c0);
;         if (t >= 2) u2[i] = *(const v4u*)(CUp + (size_t)(row - 2) * 512 + c0); }
;     const float* cw = a.in[I_CONVW] + c0; const float* gn = a.in[I_CONVN] + c0;
;     const f32x4 w0a = *(const f32x4*)(cw), w0b = *(const f32x4*)(cw + 4), w1a = *(const f32x4*)(cw + 512), w1b = *(const f32x4*)(cw + 516), w2a = *(const f32x4*)(cw + 1024), w2b = *(const f32x4*)(cw + 1028);
;     const f32x4 ga = *(const f32x4*)(gn), gb = *(const f32x4*)(gn + 4);
; #pragma unroll
;     for (int i = 0; i < NR; ++i) { const int row = r0 + i * rstride; float y[8]; float s = 0.f;
; #pragma unroll
;         for (int j = 0; j < 8; ++j) { const int sh = (j & 1) * 16; const unsigned ub = bq[i][j >> 1], x0 = u0[i][j >> 1], x1 = u1[i][j >> 1], x2 = u2[i][j >> 1];
;             const float B = __uint_as_float(((ub >> sh) & 0xffffu) << 16), c_0 = __uint_as_float(((x0 >> sh) & 0xffffu) << 16), c_1 = __uint_as_float(((x1 >> sh) & 0xffffu) << 16), c_2 = __uint_as_float(((x2 >> sh) & 0xffffu) << 16);
;             const float k0 = j < 4 ? w0a[j & 3] : w0b[j & 3], k1 = j < 4 ? w1a[j & 3] : w1b[j & 3], k2 = j < 4 ? w2a[j & 3] : w2b[j & 3];
;             y[j] = B * (k0 * c_2 + k1 * c_1 + k2 * c_0); s += y[j] * y[j]; }
;         s = wave_sum(s); const float rs = rsqrtf(s * (1.f / 512.f) + EPS);
.LBB0_757:
	global_load_dwordx4 v[72:75], v[100:101], off offset:2064
	global_load_dwordx4 v[40:43], v[100:101], off offset:2048
	global_load_dwordx4 v[76:79], v[100:101], off offset:16
	global_load_dwordx4 v[44:47], v[100:101], off
	global_load_dwordx4 v[68:71], v[104:105], off offset:16
	global_load_dwordx4 v[36:39], v[104:105], off
	global_load_dwordx4 v[16:19], v[102:103], off offset:16
	global_load_dwordx4 v[20:23], v[102:103], off
	v_lshlrev_b32_e32 v120, 16, v3
	v_and_b32_e32 v121, 0xffff0000, v3
	v_lshlrev_b32_e32 v116, 16, v87
	v_and_b32_e32 v117, 0xffff0000, v87
	v_lshlrev_b32_e32 v118, 16, v83
	v_and_b32_e32 v119, 0xffff0000, v83
	v_lshlrev_b32_e32 v122, 16, v91
	v_and_b32_e32 v123, 0xffff0000, v91
	v_lshlrev_b32_e32 v124, 16, v86
	v_and_b32_e32 v125, 0xffff0000, v86
	v_lshlrev_b32_e32 v86, 16, v82
	v_and_b32_e32 v87, 0xffff0000, v82
	v_lshlrev_b32_e32 v82, 16, v2
	v_and_b32_e32 v83, 0xffff0000, v2
	v_lshlrev_b32_e32 v2, 16, v90
	v_and_b32_e32 v3, 0xffff0000, v90
	v_lshlrev_b32_e32 v90, 16, v85
	v_and_b32_e32 v91, 0xffff0000, v85
	v_lshlrev_b32_e32 v126, 16, v81
	v_and_b32_e32 v127, 0xffff0000, v81
	v_lshlrev_b32_e32 v128, 16, v1
	v_and_b32_e32 v129, 0xffff0000, v1
	v_lshlrev_b32_e32 v130, 16, v89
	v_and_b32_e32 v131, 0xffff0000, v89
	v_lshlrev_b32_e32 v132, 16, v84
	v_and_b32_e32 v133, 0xffff0000, v84
	v_lshlrev_b32_e32 v84, 16, v80
	v_and_b32_e32 v85, 0xffff0000, v80
	v_lshlrev_b32_e32 v80, 16, v0
	v_and_b32_e32 v81, 0xffff0000, v0
	v_lshlrev_b32_e32 v0, 16, v88
	v_and_b32_e32 v1, 0xffff0000, v88
	s_waitcnt vmcnt(13)
	v_lshlrev_b32_e32 v88, 16, v67
	v_and_b32_e32 v89, 0xffff0000, v67
	s_waitcnt vmcnt(12)
	v_lshlrev_b32_e32 v134, 16, v63
	v_and_b32_e32 v135, 0xffff0000, v63
	v_lshlrev_b32_e32 v140, 16, v66
	v_and_b32_e32 v141, 0xffff0000, v66
	v_lshlrev_b32_e32 v66, 16, v62
	v_and_b32_e32 v67, 0xffff0000, v62
	v_lshlrev_b32_e32 v62, 16, v6
	v_and_b32_e32 v63, 0xffff0000, v6
	v_lshlrev_b32_e32 v136, 16, v7
	v_and_b32_e32 v137, 0xffff0000, v7
	v_lshlrev_b32_e32 v6, 16, v94
	v_and_b32_e32 v7, 0xffff0000, v94
	v_lshlrev_b32_e32 v138, 16, v95
	v_and_b32_e32 v139, 0xffff0000, v95
	v_lshlrev_b32_e32 v94, 16, v65
	v_and_b32_e32 v95, 0xffff0000, v65
	v_and_b32_e32 v65, 0xffff0000, v60
	s_add_i32 s26, s10, s58
	s_add_i32 s26, s26, s58
	s_lshl_b64 s[4:5], s[24:25], 11
	s_add_u32 s4, s18, s4
	s_addc_u32 s5, s19, s5
	s_waitcnt vmcnt(7)
	v_pk_mul_f32 v[120:121], v[74:75], v[120:121]
	s_waitcnt vmcnt(6)
	v_pk_mul_f32 v[80:81], v[40:41], v[80:81]
	v_pk_mul_f32 v[62:63], v[72:73], v[62:63]
	s_waitcnt vmcnt(5)
	v_pk_fma_f32 v[120:121], v[78:79], v[122:123], v[120:121]
	s_waitcnt vmcnt(4)
	v_pk_fma_f32 v[0:1], v[44:45], v[0:1], v[80:81]
	v_pk_fma_f32 v[6:7], v[76:77], v[6:7], v[62:63]
	s_waitcnt vmcnt(3)
	v_pk_fma_f32 v[62:63], v[70:71], v[118:119], v[120:121]
	s_waitcnt vmcnt(2)
	v_pk_fma_f32 v[0:1], v[36:37], v[84:85], v[0:1]
	v_pk_mul_f32 v[84:85], v[62:63], v[116:117]
	v_lshlrev_b32_e32 v116, 16, v5
	v_and_b32_e32 v117, 0xffff0000, v5
	v_pk_fma_f32 v[66:67], v[68:69], v[66:67], v[6:7]
	v_lshlrev_b32_e32 v118, 16, v93
	v_and_b32_e32 v119, 0xffff0000, v93
	v_pk_mul_f32 v[116:117], v[42:43], v[116:117]
	v_pk_mul_f32 v[62:63], v[66:67], v[140:141]
	v_lshlrev_b32_e32 v66, 16, v61
	v_and_b32_e32 v67, 0xffff0000, v61
	v_pk_fma_f32 v[116:117], v[46:47], v[118:119], v[116:117]
	v_and_b32_e32 v61, 0xffff0000, v4
	v_pk_fma_f32 v[66:67], v[38:39], v[66:67], v[116:117]
	v_and_b32_e32 v5, 0xffff0000, v92
	v_pk_mul_f32 v[66:67], v[66:67], v[94:95]
	v_lshlrev_b32_e32 v94, 16, v64
	v_and_b32_e32 v95, 0xffff0000, v64
	v_lshlrev_b32_e32 v64, 16, v60
	v_lshlrev_b32_e32 v60, 16, v4
	v_lshlrev_b32_e32 v4, 16, v92
	v_pk_mul_f32 v[60:61], v[40:41], v[60:61]
	v_pk_mul_f32 v[82:83], v[72:73], v[82:83]
	v_pk_fma_f32 v[4:5], v[44:45], v[4:5], v[60:61]
	v_pk_mul_f32 v[128:129], v[42:43], v[128:129]
	v_pk_fma_f32 v[4:5], v[36:37], v[64:65], v[4:5]
	v_pk_fma_f32 v[2:3], v[76:77], v[2:3], v[82:83]
	v_pk_fma_f32 v[82:83], v[46:47], v[130:131], v[128:129]
	v_pk_mul_f32 v[0:1], v[0:1], v[132:133]
	v_pk_mul_f32 v[4:5], v[4:5], v[94:95]
	v_pk_fma_f32 v[82:83], v[38:39], v[126:127], v[82:83]
	v_mov_b32_e32 v94, v5
	v_mov_b32_e32 v95, v1
	v_pk_mul_f32 v[136:137], v[74:75], v[136:137]
	v_pk_fma_f32 v[2:3], v[68:69], v[86:87], v[2:3]
	v_pk_mul_f32 v[82:83], v[82:83], v[90:91]
	v_mov_b32_e32 v92, v4
	v_mov_b32_e32 v93, v0
	v_pk_mul_f32 v[94:95], v[94:95], v[94:95]
	v_pk_fma_f32 v[80:81], v[78:79], v[138:139], v[136:137]
	v_pk_mul_f32 v[2:3], v[2:3], v[124:125]
	v_mov_b32_e32 v60, v66
	v_mov_b32_e32 v61, v82
	v_pk_fma_f32 v[92:93], v[92:93], v[92:93], v[94:95]
	v_pk_fma_f32 v[80:81], v[70:71], v[134:135], v[80:81]
	v_pk_mul_f32 v[86:87], v[2:3], v[2:3]
	v_pk_mul_f32 v[90:91], v[62:63], v[62:63]
	v_mov_b32_e32 v64, v67
	v_mov_b32_e32 v65, v83
	v_pk_fma_f32 v[60:61], v[60:61], v[60:61], v[92:93]
	v_pk_mul_f32 v[6:7], v[80:81], v[88:89]
	v_pk_fma_f32 v[60:61], v[64:65], v[64:65], v[60:61]
	v_mov_b32_e32 v64, v90
	v_mov_b32_e32 v65, v86
	v_pk_mul_f32 v[80:81], v[84:85], v[84:85]
	v_pk_mul_f32 v[88:89], v[6:7], v[6:7]
	v_pk_add_f32 v[60:61], v[64:65], v[60:61]
	v_mov_b32_e32 v86, v91
	v_pk_add_f32 v[60:61], v[86:87], v[60:61]
	v_mov_b32_e32 v64, v88
	v_mov_b32_e32 v65, v80
	v_pk_add_f32 v[60:61], v[64:65], v[60:61]
	v_mov_b32_e32 v80, v89
	v_pk_add_f32 v[60:61], v[80:81], v[60:61]
	ds_bpermute_b32 v65, v97, v61
	ds_bpermute_b32 v64, v97, v60
	s_waitcnt lgkmcnt(0)
	v_pk_add_f32 v[60:61], v[60:61], v[64:65]
	ds_bpermute_b32 v65, v110, v61
	ds_bpermute_b32 v64, v110, v60
	s_waitcnt lgkmcnt(0)
	v_pk_add_f32 v[60:61], v[60:61], v[64:65]
	ds_bpermute_b32 v65, v111, v61
	ds_bpermute_b32 v64, v111, v60
	s_waitcnt lgkmcnt(0)
; __device__ __forceinline__ unsigned pk2(float lo, float hi) { return pg8::cvt_pk_bf16(lo, hi); }
; template <int NR>
; __device__ __forceinline__ void conv_rows(const Args& a, int r0, int rstride, int lane) {
;     ...
;     for (int i = 0; i < NR; ++i) { const int row = r0 + i * rstride; float y[8]; float s = 0.f;
; #pragma unroll
;         for (int j = 0; j < 8; ++j) { const int sh = (j & 1) * 16; const unsigned ub = bq[i][j >> 1], x0 = u0[i][j >> 1], x1 = u1[i][j >> 1], x2 = u2[i][j >> 1];
;             const float B = __uint_as_float(((ub >> sh) & 0xffffu) << 16), c_0 = __uint_as_float(((x0 >> sh) & 0xffffu) << 16), c_1 = __uint_as_float(((x1 >> sh) & 0xffffu) << 16), c_2 = __uint_as_float(((x2 >> sh) & 0xffffu) << 16);
;             const float k0 = j < 4 ? w0a[j & 3] : w0b[j & 3], k1 = j < 4 ? w1a[j & 3] : w1b[j & 3], k2 = j < 4 ? w2a[j & 3] : w2b[j & 3];
;             y[j] = B * (k0 * c_2 + k1 * c_1 + k2 * c_0); s += y[j] * y[j]; }
;         s = wave_sum(s); const float rs = rsqrtf(s * (1.f / 512.f) + EPS);
;         v4u o; o.x = pk2(y[0] * rs * ga[0], y[1] * rs * ga[1]); o.y = pk2(y[2] * rs * ga[2], y[3] * rs * ga[3]); o.z = pk2(y[4] * rs * gb[0], y[5] * rs * gb[1]); o.w = pk2(y[6] * rs * gb[2], y[7] * rs * gb[3]);
;         pg8::st_wt16((bf16*)(ws + WS_MIX) + (size_t)row * 1024 + 512 + c0, o); }
	v_pk_add_f32 v[60:61], v[60:61], v[64:65]
	ds_bpermute_b32 v65, v112, v61
	ds_bpermute_b32 v64, v112, v60
	s_waitcnt lgkmcnt(0)
	v_pk_add_f32 v[60:61], v[60:61], v[64:65]
	ds_bpermute_b32 v65, v113, v61
	ds_bpermute_b32 v64, v113, v60
	s_waitcnt lgkmcnt(0)
	v_pk_add_f32 v[60:61], v[60:61], v[64:65]
	ds_bpermute_b32 v65, v114, v61
	ds_bpermute_b32 v64, v114, v60
	s_waitcnt lgkmcnt(0)
	v_pk_add_f32 v[64:65], v[60:61], v[64:65]
	v_mov_b64_e32 v[60:61], s[8:9]
	v_pk_fma_f32 v[80:81], v[64:65], s[6:7], v[60:61] op_sel_hi:[1,0,0]
	s_nop 0
	v_mul_f32_e32 v64, 0x4b800000, v81
	v_cmp_gt_f32_e32 vcc, s22, v81
	s_nop 1
	v_cndmask_b32_e32 v64, v81, v64, vcc
	v_rsq_f32_e32 v81, v64
	v_lshl_add_u64 v[64:65], s[4:5], 0, v[106:107]
	v_mul_f32_e32 v86, 0x45800000, v81
	v_cndmask_b32_e32 v86, v81, v86, vcc
	v_pk_mul_f32 v[0:1], v[0:1], v[86:87] op_sel_hi:[1,0]
	v_pk_mul_f32 v[82:83], v[82:83], v[86:87] op_sel_hi:[1,0]
	s_waitcnt vmcnt(0)
	v_pk_mul_f32 v[0:1], v[20:21], v[0:1]
	v_pk_mul_f32 v[82:83], v[22:23], v[82:83]
	v_cvt_pk_bf16_f32 v0, v0, v1
	v_cvt_pk_bf16_f32 v1, v82, v83
	v_pk_mul_f32 v[2:3], v[2:3], v[86:87] op_sel_hi:[1,0]
	v_pk_mul_f32 v[82:83], v[84:85], v[86:87] op_sel_hi:[1,0]
	v_lshlrev_b32_e32 v84, 16, v11
	v_and_b32_e32 v85, 0xffff0000, v11
	v_pk_mul_f32 v[2:3], v[16:17], v[2:3]
	v_pk_mul_f32 v[82:83], v[18:19], v[82:83]
	v_mul_f32_e32 v81, 0x4b800000, v80
	v_cmp_gt_f32_e32 vcc, s22, v80
	v_lshlrev_b32_e32 v86, 16, v59
	v_and_b32_e32 v87, 0xffff0000, v59
	v_pk_mul_f32 v[84:85], v[74:75], v[84:85]
	v_cvt_pk_bf16_f32 v2, v2, v3
	v_cvt_pk_bf16_f32 v3, v82, v83
	v_cndmask_b32_e32 v80, v80, v81, vcc
	v_lshlrev_b32_e32 v82, 16, v51
	v_and_b32_e32 v83, 0xffff0000, v51
	v_pk_fma_f32 v[84:85], v[78:79], v[86:87], v[84:85]
	v_rsq_f32_e32 v88, v80
	v_lshlrev_b32_e32 v80, 16, v55
	v_and_b32_e32 v81, 0xffff0000, v55
	v_pk_fma_f32 v[82:83], v[70:71], v[82:83], v[84:85]
	v_lshlrev_b32_e32 v84, 16, v54
	v_and_b32_e32 v85, 0xffff0000, v54
	v_lshlrev_b32_e32 v54, 16, v50
	v_and_b32_e32 v55, 0xffff0000, v50
	v_lshlrev_b32_e32 v50, 16, v10
	v_and_b32_e32 v51, 0xffff0000, v10
	v_lshlrev_b32_e32 v10, 16, v58
	v_and_b32_e32 v11, 0xffff0000, v58
	v_pk_mul_f32 v[50:51], v[72:73], v[50:51]
	v_lshlrev_b32_e32 v86, 16, v57
	v_pk_fma_f32 v[10:11], v[76:77], v[10:11], v[50:51]
	v_and_b32_e32 v87, 0xffff0000, v57
	v_pk_fma_f32 v[10:11], v[68:69], v[54:55], v[10:11]
	v_lshlrev_b32_e32 v58, 16, v49
	v_pk_mul_f32 v[10:11], v[10:11], v[84:85]
	v_lshlrev_b32_e32 v84, 16, v9
	v_and_b32_e32 v85, 0xffff0000, v9
	v_pk_mul_f32 v[84:85], v[42:43], v[84:85]
	v_and_b32_e32 v59, 0xffff0000, v49
	v_pk_fma_f32 v[84:85], v[46:47], v[86:87], v[84:85]
	v_lshlrev_b32_e32 v54, 16, v53
	v_and_b32_e32 v55, 0xffff0000, v53
	v_pk_fma_f32 v[58:59], v[38:39], v[58:59], v[84:85]
	v_and_b32_e32 v53, 0xffff0000, v48
	v_pk_mul_f32 v[54:55], v[58:59], v[54:55]
	v_lshlrev_b32_e32 v58, 16, v52
	v_and_b32_e32 v59, 0xffff0000, v52
	v_lshlrev_b32_e32 v52, 16, v48
	v_lshlrev_b32_e32 v48, 16, v8
	v_and_b32_e32 v49, 0xffff0000, v8
	v_lshlrev_b32_e32 v8, 16, v56
	v_and_b32_e32 v9, 0xffff0000, v56
	v_pk_mul_f32 v[48:49], v[40:41], v[48:49]
	v_lshlrev_b32_e32 v56, 16, v31
	v_pk_fma_f32 v[8:9], v[44:45], v[8:9], v[48:49]
	v_lshlrev_b32_e32 v48, 16, v35
	v_pk_fma_f32 v[8:9], v[36:37], v[52:53], v[8:9]
	v_lshlrev_b32_e32 v52, 16, v15
	v_and_b32_e32 v53, 0xffff0000, v15
	v_and_b32_e32 v49, 0xffff0000, v35
	v_pk_mul_f32 v[52:53], v[74:75], v[52:53]
	v_and_b32_e32 v57, 0xffff0000, v31
	v_pk_fma_f32 v[48:49], v[78:79], v[48:49], v[52:53]
	v_and_b32_e32 v35, 0xffff0000, v14
	v_pk_fma_f32 v[48:49], v[70:71], v[56:57], v[48:49]
	v_lshlrev_b32_e32 v56, 16, v34
	v_and_b32_e32 v57, 0xffff0000, v34
	v_lshlrev_b32_e32 v34, 16, v14
	v_pk_mul_f32 v[14:15], v[72:73], v[34:35]
	v_lshlrev_b32_e32 v34, 16, v30
	v_pk_fma_f32 v[14:15], v[76:77], v[56:57], v[14:15]
	v_and_b32_e32 v35, 0xffff0000, v30
	v_pk_fma_f32 v[14:15], v[68:69], v[34:35], v[14:15]
	v_lshlrev_b32_e32 v30, 16, v26
	v_and_b32_e32 v31, 0xffff0000, v26
	v_lshlrev_b32_e32 v34, 16, v13
	v_and_b32_e32 v35, 0xffff0000, v13
	v_pk_mul_f32 v[14:15], v[14:15], v[30:31]
	v_lshlrev_b32_e32 v30, 16, v33
	v_and_b32_e32 v31, 0xffff0000, v33
	v_pk_mul_f32 v[34:35], v[42:43], v[34:35]
	v_and_b32_e32 v33, 0xffff0000, v12
	v_pk_fma_f32 v[30:31], v[46:47], v[30:31], v[34:35]
	v_lshlrev_b32_e32 v34, 16, v29
	v_and_b32_e32 v35, 0xffff0000, v29
	v_pk_fma_f32 v[30:31], v[38:39], v[34:35], v[30:31]
	v_lshlrev_b32_e32 v34, 16, v25
	v_and_b32_e32 v35, 0xffff0000, v25
	v_pk_mul_f32 v[30:31], v[30:31], v[34:35]
	v_lshlrev_b32_e32 v34, 16, v32
	v_and_b32_e32 v35, 0xffff0000, v32
	v_lshlrev_b32_e32 v32, 16, v12
	v_pk_mul_f32 v[12:13], v[40:41], v[32:33]
	v_lshlrev_b32_e32 v32, 16, v28
	v_pk_fma_f32 v[12:13], v[44:45], v[34:35], v[12:13]
	v_and_b32_e32 v33, 0xffff0000, v28
	v_pk_fma_f32 v[12:13], v[36:37], v[32:33], v[12:13]
	v_lshlrev_b32_e32 v28, 16, v24
	v_and_b32_e32 v29, 0xffff0000, v24
	v_pk_mul_f32 v[8:9], v[8:9], v[58:59]
	v_pk_mul_f32 v[12:13], v[12:13], v[28:29]
	v_mov_b32_e32 v35, v9
	v_mov_b32_e32 v34, v13
	v_mov_b32_e32 v32, v12
	v_mov_b32_e32 v33, v8
	v_pk_mul_f32 v[34:35], v[34:35], v[34:35]
	v_mov_b32_e32 v24, v30
	v_mov_b32_e32 v25, v54
	v_pk_fma_f32 v[32:33], v[32:33], v[32:33], v[34:35]
	v_pk_mul_f32 v[50:51], v[10:11], v[10:11]
	v_lshlrev_b32_e32 v58, 16, v27
	v_and_b32_e32 v59, 0xffff0000, v27
	v_pk_mul_f32 v[26:27], v[14:15], v[14:15]
	v_mov_b32_e32 v28, v31
	v_mov_b32_e32 v29, v55
	v_pk_fma_f32 v[24:25], v[24:25], v[24:25], v[32:33]
	v_pk_mul_f32 v[80:81], v[82:83], v[80:81]
	v_pk_mul_f32 v[48:49], v[48:49], v[58:59]
	v_pk_fma_f32 v[24:25], v[28:29], v[28:29], v[24:25]
	v_mov_b32_e32 v28, v26
	v_mov_b32_e32 v29, v50
	v_pk_mul_f32 v[82:83], v[80:81], v[80:81]
	v_pk_mul_f32 v[52:53], v[48:49], v[48:49]
	v_pk_add_f32 v[24:25], v[28:29], v[24:25]
	v_mov_b32_e32 v50, v27
	v_pk_add_f32 v[24:25], v[50:51], v[24:25]
	v_mov_b32_e32 v26, v52
	v_mov_b32_e32 v27, v82
	v_pk_add_f32 v[24:25], v[26:27], v[24:25]
	v_mov_b32_e32 v82, v53
	v_pk_add_f32 v[24:25], v[82:83], v[24:25]
	ds_bpermute_b32 v27, v97, v25
	ds_bpermute_b32 v26, v97, v24
	v_add_co_u32_e64 v28, s[4:5], s23, v64
	s_nop 1
	v_addc_co_u32_e64 v29, s[4:5], 0, v65, s[4:5]
	global_store_dwordx4 v[28:29], v[0:3], off offset:1024 sc1
	s_lshl_b64 s[4:5], s[10:11], 11
	s_add_u32 s4, s18, s4
	s_waitcnt lgkmcnt(0)
; __device__ __forceinline__ unsigned pk2(float lo, float hi) { return pg8::cvt_pk_bf16(lo, hi); }
; template <int NR>
; __device__ __forceinline__ void conv_rows(const Args& a, int r0, int rstride, int lane) {
;     ...
;     for (int i = 0; i < NR; ++i) { const int row = r0 + i * rstride; float y[8]; float s = 0.f;
; #pragma unroll
;         for (int j = 0; j < 8; ++j) { const int sh = (j & 1) * 16; const unsigned ub = bq[i][j >> 1], x0 = u0[i][j >> 1], x1 = u1[i][j >> 1], x2 = u2[i][j >> 1];
;             const float B = __uint_as_float(((ub >> sh) & 0xffffu) << 16), c_0 = __uint_as_float(((x0 >> sh) & 0xffffu) << 16), c_1 = __uint_as_float(((x1 >> sh) & 0xffffu) << 16), c_2 = __uint_as_float(((x2 >> sh) & 0xffffu) << 16);
;             const float k0 = j < 4 ? w0a[j & 3] : w0b[j & 3], k1 = j < 4 ? w1a[j & 3] : w1b[j & 3], k2 = j < 4 ? w2a[j & 3] : w2b[j & 3];
;             y[j] = B * (k0 * c_2 + k1 * c_1 + k2 * c_0); s += y[j] * y[j]; }
;         s = wave_sum(s); const float rs = rsqrtf(s * (1.f / 512.f) + EPS);
;         v4u o; o.x = pk2(y[0] * rs * ga[0], y[1] * rs * ga[1]); o.y = pk2(y[2] * rs * ga[2], y[3] * rs * ga[3]); o.z = pk2(y[4] * rs * gb[0], y[5] * rs * gb[1]); o.w = pk2(y[6] * rs * gb[2], y[7] * rs * gb[3]);
;         pg8::st_wt16((bf16*)(ws + WS_MIX) + (size_t)row * 1024 + 512 + c0, o); }
	v_pk_add_f32 v[2:3], v[24:25], v[26:27]
	ds_bpermute_b32 v25, v110, v3
	ds_bpermute_b32 v24, v110, v2
	v_mul_f32_e32 v0, 0x45800000, v88
	v_cndmask_b32_e32 v28, v88, v0, vcc
	v_pk_mul_f32 v[0:1], v[4:5], v[28:29] op_sel_hi:[1,0]
	v_pk_mul_f32 v[4:5], v[66:67], v[28:29] op_sel_hi:[1,0]
	s_waitcnt lgkmcnt(0)
	v_pk_add_f32 v[2:3], v[2:3], v[24:25]
	ds_bpermute_b32 v25, v111, v3
	ds_bpermute_b32 v24, v111, v2
	v_pk_mul_f32 v[0:1], v[20:21], v[0:1]
	v_pk_mul_f32 v[4:5], v[22:23], v[4:5]
	v_cvt_pk_bf16_f32 v0, v0, v1
	v_cvt_pk_bf16_f32 v1, v4, v5
	s_waitcnt lgkmcnt(0)
	v_pk_add_f32 v[24:25], v[2:3], v[24:25]
	ds_bpermute_b32 v27, v112, v25
	ds_bpermute_b32 v26, v112, v24
	v_pk_mul_f32 v[4:5], v[62:63], v[28:29] op_sel_hi:[1,0]
	s_addc_u32 s5, s19, s5
	v_pk_mul_f32 v[4:5], v[16:17], v[4:5]
	s_nop 0
	v_cvt_pk_bf16_f32 v2, v4, v5
	v_pk_mul_f32 v[4:5], v[6:7], v[28:29] op_sel_hi:[1,0]
	s_nop 0
	v_pk_mul_f32 v[4:5], v[18:19], v[4:5]
	s_nop 0
	v_cvt_pk_bf16_f32 v3, v4, v5
	s_waitcnt lgkmcnt(0)
	v_pk_add_f32 v[4:5], v[24:25], v[26:27]
	ds_bpermute_b32 v7, v113, v5
	ds_bpermute_b32 v6, v113, v4
	v_lshl_add_u64 v[24:25], s[4:5], 0, v[106:107]
	v_add_co_u32_e32 v24, vcc, s23, v24
	s_lshl_b64 s[4:5], s[14:15], 11
	s_waitcnt lgkmcnt(0)
	v_pk_add_f32 v[4:5], v[4:5], v[6:7]
	ds_bpermute_b32 v7, v114, v5
	ds_bpermute_b32 v6, v114, v4
	v_addc_co_u32_e32 v25, vcc, 0, v25, vcc
	global_store_dwordx4 v[24:25], v[0:3], off offset:1024 sc1
	s_add_u32 s4, s18, s4
	s_addc_u32 s5, s19, s5
	s_waitcnt lgkmcnt(0)
	v_pk_add_f32 v[0:1], v[4:5], v[6:7]
	v_lshl_add_u64 v[6:7], s[4:5], 0, v[106:107]
	v_pk_fma_f32 v[4:5], v[0:1], s[6:7], v[60:61] op_sel_hi:[1,0,0]
	s_nop 0
	v_mul_f32_e32 v0, 0x4b800000, v5
	v_cmp_gt_f32_e32 vcc, s22, v5
	s_nop 1
	v_cndmask_b32_e32 v0, v5, v0, vcc
	v_rsq_f32_e32 v0, v0
	v_mul_f32_e32 v5, 0x4b800000, v4
	v_mul_f32_e32 v1, 0x45800000, v0
	v_cndmask_b32_e32 v24, v0, v1, vcc
	v_pk_mul_f32 v[0:1], v[8:9], v[24:25] op_sel_hi:[1,0]
	v_pk_mul_f32 v[2:3], v[54:55], v[24:25] op_sel_hi:[1,0]
	v_pk_mul_f32 v[0:1], v[20:21], v[0:1]
	v_pk_mul_f32 v[2:3], v[22:23], v[2:3]
	v_cvt_pk_bf16_f32 v0, v0, v1
	v_cvt_pk_bf16_f32 v1, v2, v3
	v_pk_mul_f32 v[2:3], v[10:11], v[24:25] op_sel_hi:[1,0]
	v_pk_mul_f32 v[8:9], v[80:81], v[24:25] op_sel_hi:[1,0]
	v_cmp_gt_f32_e32 vcc, s22, v4
	v_pk_mul_f32 v[2:3], v[16:17], v[2:3]
	v_pk_mul_f32 v[8:9], v[18:19], v[8:9]
	v_cndmask_b32_e32 v4, v4, v5, vcc
	v_cvt_pk_bf16_f32 v2, v2, v3
	v_cvt_pk_bf16_f32 v3, v8, v9
	v_rsq_f32_e32 v8, v4
	v_add_co_u32_e64 v4, s[4:5], s23, v6
	s_nop 1
	v_addc_co_u32_e64 v5, s[4:5], 0, v7, s[4:5]
	global_store_dwordx4 v[4:5], v[0:3], off offset:1024 sc1
	s_lshl_b64 s[4:5], s[20:21], 11
	s_add_u32 s4, s18, s4
	v_mul_f32_e32 v0, 0x45800000, v8
	v_cndmask_b32_e32 v4, v8, v0, vcc
	v_pk_mul_f32 v[0:1], v[12:13], v[4:5] op_sel_hi:[1,0]
	v_pk_mul_f32 v[2:3], v[30:31], v[4:5] op_sel_hi:[1,0]
	v_pk_mul_f32 v[0:1], v[20:21], v[0:1]
	v_pk_mul_f32 v[2:3], v[22:23], v[2:3]
	v_cvt_pk_bf16_f32 v0, v0, v1
	v_cvt_pk_bf16_f32 v1, v2, v3
	v_pk_mul_f32 v[2:3], v[14:15], v[4:5] op_sel_hi:[1,0]
	v_pk_mul_f32 v[4:5], v[48:49], v[4:5] op_sel_hi:[1,0]
	v_pk_mul_f32 v[2:3], v[16:17], v[2:3]
	v_pk_mul_f32 v[4:5], v[18:19], v[4:5]
	s_addc_u32 s5, s19, s5
	v_cvt_pk_bf16_f32 v2, v2, v3
	v_cvt_pk_bf16_f32 v3, v4, v5
	v_lshl_add_u64 v[4:5], s[4:5], 0, v[106:107]
	v_add_co_u32_e32 v4, vcc, 0xe000000, v4
	s_add_i32 s24, s26, s58
	s_nop 0
	v_addc_co_u32_e32 v5, vcc, 0, v5, vcc
	s_cmpk_gt_i32 s24, 0x3fff
	global_store_dwordx4 v[4:5], v[0:3], off offset:1024 sc1
	s_cbranch_scc1 .LBB0_939

; #define LAS __attribute__((address_space(3)))
; __device__ __forceinline__ unsigned pk2(float lo, float hi) { return pg8::cvt_pk_bf16(lo, hi); }
; #define LBAR() do { asm volatile("s_waitcnt lgkmcnt(0)" ::: "memory"); __builtin_amdgcn_s_barrier(); asm volatile("" ::: "memory"); } while (0)
; __device__ __forceinline__ void hg_c2_unit(const Args& a, const float* Gp, LAS unsigned char* lds, int unit, int tid) {
;     ...
; #pragma unroll
;         for (int kt = 0; kt < 8; ++kt) { const f32x4 d = *(const LAS f32x4*)(dl + 16 * kt + 4 * lq); S[kt] = S[kt] * d;
; #pragma unroll
;             for (int ss = 0; ss < 2; ++ss) { const bf16x8 x = *(const LAS bf16x8*)(KPt + (16 * kt + l15) * 72 + 32 * ss + 8 * lq), y = *(const LAS bf16x8*)(Vt + (16 * wave + l15) * 72 + 32 * ss + 8 * lq);
;                 S[kt] = __builtin_amdgcn_mfma_f32_16x16x32_bf16(x, y, S[kt], 0, 0, 0); } }
;         LBAR();
;         const float rs = rsqrtf((part[t] + part[64 + t]) * (1.f / 128.f) + EPS);
;         const size_t orow = (size_t)(row0 + t);
; #pragma unroll
;         for (int n = 0; n < 4; ++n) { const int v0 = 64 * vh + 16 * n + 4 * lq; const v2u gsw = gsw4[n]; const f32x4 gn = gn4[n];
;             const float o0 = acc[n][0] * rs * gn[0] * __uint_as_float(gsw.x << 16), o1 = acc[n][1] * rs * gn[1] * __uint_as_float(gsw.x & 0xffff0000u);
;             const float o2 = acc[n][2] * rs * gn[2] * __uint_as_float(gsw.y << 16), o3 = acc[n][3] * rs * gn[3] * __uint_as_float(gsw.y & 0xffff0000u);
;             v2u w; w.x = pk2(o0, o1); w.y = pk2(o2, o3); pg8::st_wt8((bf16*)(ws + WS_MIX) + orow * 1024 + h * 128 + v0, w); }
;         LBAR();
.LBB0_919:
	s_or_b64 exec, exec, s[34:35]
	ds_read_b128 v[96:99], v206
	ds_read_b128 v[104:107], v205
	ds_read_b128 v[108:111], v206 offset:64
	ds_read_b128 v[116:119], v194 offset:56320
	ds_read_b128 v[228:231], v194 offset:56384
	ds_read_b128 v[232:235], v205 offset:64
	s_waitcnt lgkmcnt(4)
	v_pk_mul_f32 v[10:11], v[10:11], v[106:107]
	v_pk_mul_f32 v[8:9], v[8:9], v[104:105]
	ds_read_b128 v[104:107], v206 offset:2368
	v_lshlrev_b64 v[82:83], 11, v[82:83]
	s_waitcnt lgkmcnt(3)
	v_mfma_f32_16x16x32_bf16 v[8:11], v[96:99], v[116:119], v[8:11]
	ds_read_b128 v[96:99], v206 offset:2304
	s_waitcnt lgkmcnt(2)
	v_pk_mul_f32 v[18:19], v[18:19], v[234:235]
	v_pk_mul_f32 v[16:17], v[16:17], v[232:233]
	v_mfma_f32_16x16x32_bf16 v[8:11], v[108:111], v[228:231], v[8:11]
	s_add_i32 s36, s36, 64
	s_cmpk_lg_i32 s36, 0x100
	s_waitcnt lgkmcnt(0)
	v_mfma_f32_16x16x32_bf16 v[16:19], v[96:99], v[116:119], v[16:19]
	ds_read_b128 v[96:99], v206 offset:4608
	ds_read_b128 v[108:111], v205 offset:128
	s_waitcnt lgkmcnt(0)
	v_pk_mul_f32 v[26:27], v[26:27], v[110:111]
	v_pk_mul_f32 v[24:25], v[24:25], v[108:109]
	v_mfma_f32_16x16x32_bf16 v[16:19], v[104:107], v[228:231], v[16:19]
	ds_read_b128 v[104:107], v206 offset:4672
	ds_read_b128 v[232:235], v205 offset:192
	s_waitcnt lgkmcnt(0)
	v_pk_mul_f32 v[34:35], v[34:35], v[234:235]
	v_mfma_f32_16x16x32_bf16 v[24:27], v[96:99], v[116:119], v[24:27]
	ds_read_b128 v[96:99], v206 offset:6912
	v_pk_mul_f32 v[32:33], v[32:33], v[232:233]
	v_mfma_f32_16x16x32_bf16 v[24:27], v[104:107], v[228:231], v[24:27]
	ds_read_b128 v[104:107], v206 offset:6976
	s_waitcnt lgkmcnt(1)
	v_mfma_f32_16x16x32_bf16 v[32:35], v[96:99], v[116:119], v[32:35]
	ds_read_b128 v[96:99], v206 offset:9216
	ds_read_b128 v[108:111], v205 offset:256
	s_waitcnt lgkmcnt(0)
	v_pk_mul_f32 v[42:43], v[42:43], v[110:111]
	v_pk_mul_f32 v[40:41], v[40:41], v[108:109]
	v_mfma_f32_16x16x32_bf16 v[32:35], v[104:107], v[228:231], v[32:35]
	ds_read_b128 v[104:107], v206 offset:9280
	ds_read_b128 v[232:235], v205 offset:320
	s_waitcnt lgkmcnt(0)
	v_pk_mul_f32 v[50:51], v[50:51], v[234:235]
	v_mfma_f32_16x16x32_bf16 v[40:43], v[96:99], v[116:119], v[40:43]
	ds_read_b128 v[96:99], v206 offset:11520
	ds_read_b128 v[108:111], v206 offset:11584
	v_pk_mul_f32 v[48:49], v[48:49], v[232:233]
	v_mfma_f32_16x16x32_bf16 v[40:43], v[104:107], v[228:231], v[40:43]
	ds_read_b128 v[104:107], v206 offset:13824
	s_waitcnt lgkmcnt(2)
	v_mfma_f32_16x16x32_bf16 v[48:51], v[96:99], v[116:119], v[48:51]
	ds_read_b128 v[96:99], v205 offset:384
	ds_read_b128 v[232:235], v206 offset:13888
	s_waitcnt lgkmcnt(1)
	v_pk_mul_f32 v[58:59], v[58:59], v[98:99]
	v_pk_mul_f32 v[56:57], v[56:57], v[96:97]
	v_mfma_f32_16x16x32_bf16 v[48:51], v[108:111], v[228:231], v[48:51]
	ds_read_b128 v[108:111], v205 offset:448
	s_waitcnt lgkmcnt(0)
	v_pk_mul_f32 v[14:15], v[14:15], v[110:111]
	v_mfma_f32_16x16x32_bf16 v[56:59], v[104:107], v[116:119], v[56:59]
	ds_read_b128 v[96:99], v206 offset:16128
	ds_read_b128 v[104:107], v206 offset:16192
	s_waitcnt lgkmcnt(0)
	s_barrier
	ds_read2st64_b32 v[90:91], v207 offset0:10 offset1:11
	v_pk_mul_f32 v[12:13], v[12:13], v[108:109]
	v_mfma_f32_16x16x32_bf16 v[56:59], v[232:235], v[228:231], v[56:59]
	s_waitcnt lgkmcnt(0)
	v_add_f32_e32 v90, v90, v91
	v_fmamk_f32 v90, v90, 0x3c000000, v210
	v_mul_f32_e32 v91, 0x4b800000, v90
	v_cmp_gt_f32_e32 vcc, s88, v90
	v_mfma_f32_16x16x32_bf16 v[12:15], v[96:99], v[116:119], v[12:15]
	s_nop 0
	v_cndmask_b32_e32 v90, v90, v91, vcc
	v_rsq_f32_e32 v90, v90
	v_mfma_f32_16x16x32_bf16 v[12:15], v[104:107], v[228:231], v[12:15]
	v_mul_f32_e32 v91, 0x45800000, v90
	v_cndmask_b32_e32 v90, v90, v91, vcc
	v_pk_mul_f32 v[68:69], v[68:69], v[90:91] op_sel_hi:[1,0]
	s_waitcnt vmcnt(7)
	v_pk_mul_f32 v[44:45], v[44:45], v[68:69]
	s_waitcnt vmcnt(5)
	v_lshlrev_b32_e32 v68, 16, v80
	v_and_b32_e32 v69, 0xffff0000, v80
	v_pk_mul_f32 v[44:45], v[44:45], v[68:69]
	v_pk_mul_f32 v[68:69], v[70:71], v[90:91] op_sel_hi:[1,0]
	v_cvt_pk_bf16_f32 v44, v44, v45
	v_pk_mul_f32 v[46:47], v[46:47], v[68:69]
	v_lshlrev_b32_e32 v68, 16, v81
	v_and_b32_e32 v69, 0xffff0000, v81
	v_pk_mul_f32 v[46:47], v[46:47], v[68:69]
	s_nop 0
	v_cvt_pk_bf16_f32 v45, v46, v47
	v_lshl_add_u64 v[46:47], v[6:7], 0, v[82:83]
	global_store_dwordx2 v[46:47], v[44:45], off sc1
	v_pk_mul_f32 v[44:45], v[64:65], v[90:91] op_sel_hi:[1,0]
	s_nop 0
	v_pk_mul_f32 v[36:37], v[36:37], v[44:45]
	s_waitcnt vmcnt(5)
	v_lshlrev_b32_e32 v44, 16, v78
	v_and_b32_e32 v45, 0xffff0000, v78
	v_pk_mul_f32 v[36:37], v[36:37], v[44:45]
	v_pk_mul_f32 v[44:45], v[66:67], v[90:91] op_sel_hi:[1,0]
	v_cvt_pk_bf16_f32 v36, v36, v37
	v_pk_mul_f32 v[38:39], v[38:39], v[44:45]
	v_lshlrev_b32_e32 v44, 16, v79
	v_and_b32_e32 v45, 0xffff0000, v79
	v_pk_mul_f32 v[38:39], v[38:39], v[44:45]
	s_nop 0
	v_cvt_pk_bf16_f32 v37, v38, v39
	global_store_dwordx2 v[46:47], v[36:37], off offset:32 sc1
	v_pk_mul_f32 v[36:37], v[60:61], v[90:91] op_sel_hi:[1,0]
	s_waitcnt vmcnt(3)
	v_pk_mul_f32 v[28:29], v[28:29], v[36:37]
	v_lshlrev_b32_e32 v36, 16, v76
	v_and_b32_e32 v37, 0xffff0000, v76
	v_pk_mul_f32 v[28:29], v[28:29], v[36:37]
	v_pk_mul_f32 v[36:37], v[62:63], v[90:91] op_sel_hi:[1,0]
	v_cvt_pk_bf16_f32 v28, v28, v29
	v_pk_mul_f32 v[30:31], v[30:31], v[36:37]
	v_lshlrev_b32_e32 v36, 16, v77
	v_and_b32_e32 v37, 0xffff0000, v77
	v_pk_mul_f32 v[30:31], v[30:31], v[36:37]
	s_nop 0
	v_cvt_pk_bf16_f32 v29, v30, v31
	global_store_dwordx2 v[46:47], v[28:29], off offset:64 sc1
	v_pk_mul_f32 v[28:29], v[52:53], v[90:91] op_sel_hi:[1,0]
	s_waitcnt vmcnt(3)
	v_pk_mul_f32 v[20:21], v[20:21], v[28:29]
	v_lshlrev_b32_e32 v28, 16, v74
	v_and_b32_e32 v29, 0xffff0000, v74
	v_pk_mul_f32 v[20:21], v[20:21], v[28:29]
	v_pk_mul_f32 v[28:29], v[54:55], v[90:91] op_sel_hi:[1,0]
	v_cvt_pk_bf16_f32 v20, v20, v21
	v_pk_mul_f32 v[22:23], v[22:23], v[28:29]
	v_lshlrev_b32_e32 v28, 16, v75
	v_and_b32_e32 v29, 0xffff0000, v75
	v_pk_mul_f32 v[22:23], v[22:23], v[28:29]
	s_nop 0
	v_cvt_pk_bf16_f32 v21, v22, v23
	global_store_dwordx2 v[46:47], v[20:21], off offset:96 sc1
	s_waitcnt lgkmcnt(0)
	s_barrier
	s_cbranch_scc0 .LBB0_778

; #define SEAM(k) do { if (IN(k) && IN((k) + 1)) flat_barrier((unsigned*)(ws + WS_BAR + 65536), fgen, (unsigned)G); } while (0)
; #define SEAM(k) do { if (IN(k) && IN((k) + 1)) xcd_barrier(xbar); } while (0)
; __global__ void __launch_bounds__(NT, 2) hymba_fwd(Args args) {
;     ...
;     if (IN(5)) _Pragma("unroll") for (int rep = 0; rep < NREP(5); ++rep) {
;         if (M % (4 * NGW) == 0) { for (int r = gw; r < M; r += 4 * NGW) conv_rows<4>(args, r, NGW, lane); } else { for (int r = gw; r < M; r += NGW) conv_rows<1>(args, r, NGW, lane); }
;         for (int u = vcu; u < 256; u += G) hg_c2_unit(args, args.out, lds, u, tid);
;     }
;     SEAM(5);
;     if (IN(7)) {
;         pg8::Gemm g{(const bf16*)(ws + WS_MIX), (const bf16*)(ws + WS_WOUT), M, D, D}; pg8::StaticOrder S; S.init(M, D, G, bx);
.Lgb5_wait:
	s_mov_b32 s101, s17
	s_and_b32 s14, s2, 7
	s_lshr_b32 s18, s3, 3
	s_mul_i32 s14, s14, s18
	s_lshr_b32 s18, s2, 3
	s_add_i32 s18, s14, s18
	s_lshr_b32 s14, s18, 6
	s_lshl_b32 s14, s14, 4
	s_and_b32 s15, s18, 15
	s_or_b32 s14, s14, s15
	s_lshl_b32 s14, s14, 6
	s_add_i32 s14, s14, 0x9000
	v_mov_b32_e32 v0, s14
	global_atomic_add v0, v1, s[46:47]
	s_lshr_b32 s14, s18, 5
	s_lshl_b32 s14, s14, 6
	s_add_i32 s14, s14, 0x9000
	v_mov_b32_e32 v0, s14
	global_atomic_add v0, v1, s[46:47]
	global_atomic_add v0, v1, s[46:47] offset:512
	global_atomic_add v0, v1, s[46:47] offset:1024
	global_atomic_add v0, v1, s[46:47] offset:1536
	global_atomic_add v0, v1, s[46:47] offset:2048
	global_atomic_add v0, v1, s[46:47] offset:2560
	global_atomic_add v0, v1, s[46:47] offset:3072
	global_atomic_add v0, v1, s[46:47] offset:3584
	s_and_b32 s14, s2, 7
	s_lshl_b32 s14, s14, 3
	s_bfe_u32 s15, s2, 0x30003
	s_or_b32 s14, s14, s15
	s_lshl_b32 s14, s14, 6
	s_add_i32 s14, s14, 0x9000
	v_mov_b32_e32 v0, s14
.Lgb5_ppoll:
	global_load_dword v4, v0, s[46:47] sc1
	s_waitcnt vmcnt(0)
	v_readfirstlane_b32 s14, v4
	s_cmp_ge_u32 s14, 36
	s_cbranch_scc1 .Lgb5_acq
	s_sleep 1
	s_add_i32 s19, s19, 1
	s_cmp_lt_u32 s19, 20000
	s_cbranch_scc1 .Lgb5_ppoll

; #define PG8_STAGE(bufoff, gbase, voff) do { _Pragma("unroll") for (int _i = 0; _i < 2; ++_i) \
;         __builtin_amdgcn_global_load_lds((const unsigned*)((const char*)(gbase) + (voff)[_i]), (PG8_LAS unsigned*)(lds + (bufoff) + ldsw + _i * 8192), 16, 0, 0); } while (0)
; #define PG8_LDA(dst, b, h) do { _Pragma("unroll") for (int m = 0; m < 4; ++m) _Pragma("unroll") for (int k = 0; k < 2; ++k) dst[m][k] = *(const PG8_LAS bf16x8*)(lds + PG8_SA(b, h) + aoff + m * 2048 + k * 1024); } while (0)
; #define PG8_LDB(dst, b, h) do { _Pragma("unroll") for (int n = 0; n < 2; ++n) _Pragma("unroll") for (int k = 0; k < 2; ++k) dst[n][k] = *(const PG8_LAS bf16x8*)(lds + PG8_SB(b, h) + boff + n * 2048 + k * 1024); } while (0)
; #define PG8_MMA(ai, bj, At, Bt) do { __builtin_amdgcn_s_setprio(1); _Pragma("unroll") for (int m = 0; m < 4; ++m) _Pragma("unroll") for (int n = 0; n < 2; ++n) _Pragma("unroll") for (int k = 0; k < 2; ++k) \
;         acc[ai][bj][m][n] = __builtin_amdgcn_mfma_f32_16x16x32_bf16(Bt[n][k], At[m][k], acc[ai][bj][m][n], 0, 0, 0); __builtin_amdgcn_s_setprio(0); } while (0)
; #define PG8_WAIT_V(n) asm volatile("s_waitcnt vmcnt(" #n ")" ::: "memory")
; #define PG8_BAR __builtin_amdgcn_s_barrier()
; template <class Epi, class Sched, bool ALIGN_EPI = false, bool SP2 = false>
; __device__ __forceinline__ void gemm_phase(PG8_LAS unsigned char* lds, const Gemm g, const Sched& S, const Epi& E) {
;     ...
;         for (int t = 0; t < nt; t += 2) {
;             const bool last = (t == nt - 2);
;             const char* a1 = cA + (size_t)(t + 1) * kstep;
;             const char* a2 = last ? nA : cA + (size_t)(t + 2) * kstep; const char* b2 = last ? nB : cB + (size_t)(t + 2) * kstep;
;             const char* a3 = a2 + kstep; const char* b3 = b2 + kstep;
;             if (last && has_next) S.a_ready(nxt);
;             if constexpr (SP2) {
;             PG8_LDB(B0, 0, 0); PG8_LDB(B1, 0, 1); PG8_SCHED; PG8_LDA(At, 0, 0); PG8_STAGE(PG8_SA(1, 1), a1 + hstep, voffA);
;             PG8_WAIT_V(8); PG8_WAIT_L(0); PG8_BAR; PG8_MMA(0, 0, At, B0); PG8_MMA(0, 1, At, B1); PG8_BAR; PG8_SCHED;
;             PG8_LDA(At, 0, 1); PG8_STAGE(PG8_SB(0, 0), b2, voffB); PG8_STAGE(PG8_SB(0, 1), b2 + hstep, voffB); PG8_STAGE(PG8_SA(0, 0), a2, voffA);
;             PG8_WAIT_V(8); PG8_WAIT_L(0); PG8_BAR; PG8_MMA(1, 0, At, B0); PG8_MMA(1, 1, At, B1); PG8_BAR; PG8_SCHED;
.LBB0_1271:
	ds_read_b128 v[144:147], v155
	ds_read_b128 v[148:151], v155 offset:1024
	ds_read_b128 v[160:163], v155 offset:2048
	ds_read_b128 v[164:167], v155 offset:3072
	ds_read_b128 v[168:171], v156
	ds_read_b128 v[172:175], v156 offset:1024
	ds_read_b128 v[176:179], v156 offset:2048
	ds_read_b128 v[180:183], v156 offset:3072
	s_add_u32 s36, s34, 0xfffc0080
	s_addc_u32 s37, s35, -1
	s_cmp_eq_u32 s84, 12
	s_cselect_b32 s39, s27, s37
	s_cselect_b32 s38, s80, s36
	s_cselect_b32 s37, s25, s83
	s_cselect_b32 s36, s81, s82
	v_lshl_add_u64 v[218:219], s[34:35], 0, v[136:137]
	s_add_i32 m0, s67, 0xc000
	ds_read_b128 v[184:187], v157
	ds_read_b128 v[188:191], v157 offset:1024
	ds_read_b128 v[192:195], v157 offset:2048
	ds_read_b128 v[196:199], v157 offset:3072
	ds_read_b128 v[200:203], v157 offset:4096
	ds_read_b128 v[204:207], v157 offset:5120
	ds_read_b128 v[210:213], v157 offset:6144
	ds_read_b128 v[214:217], v157 offset:7168
	global_load_lds_dwordx4 v[218:219], off
	v_lshl_add_u64 v[218:219], s[34:35], 0, v[138:139]
	s_add_i32 m0, s67, 0xe000
	s_nop 0
	global_load_lds_dwordx4 v[218:219], off
	s_waitcnt vmcnt(8)
	s_waitcnt lgkmcnt(0)
	s_barrier
	s_setprio 1
	s_waitcnt lgkmcnt(0)
	v_mfma_f32_16x16x32_bf16 v[124:127], v[144:147], v[184:187], v[124:127]
	v_mfma_f32_16x16x32_bf16 v[120:123], v[160:163], v[184:187], v[120:123]
	v_mfma_f32_16x16x32_bf16 v[108:111], v[144:147], v[192:195], v[108:111]
	v_mfma_f32_16x16x32_bf16 v[104:107], v[160:163], v[192:195], v[104:107]
	v_mfma_f32_16x16x32_bf16 v[92:95], v[144:147], v[200:203], v[92:95]
	v_mfma_f32_16x16x32_bf16 v[88:91], v[160:163], v[200:203], v[88:91]
	v_mfma_f32_16x16x32_bf16 v[76:79], v[144:147], v[210:213], v[76:79]
	v_mfma_f32_16x16x32_bf16 v[72:75], v[160:163], v[210:213], v[72:75]
	v_mfma_f32_16x16x32_bf16 v[124:127], v[148:151], v[188:191], v[124:127]
	v_mfma_f32_16x16x32_bf16 v[120:123], v[164:167], v[188:191], v[120:123]
	v_mfma_f32_16x16x32_bf16 v[108:111], v[148:151], v[196:199], v[108:111]
	v_mfma_f32_16x16x32_bf16 v[104:107], v[164:167], v[196:199], v[104:107]
	v_mfma_f32_16x16x32_bf16 v[92:95], v[148:151], v[204:207], v[92:95]
	v_mfma_f32_16x16x32_bf16 v[88:91], v[164:167], v[204:207], v[88:91]
	v_mfma_f32_16x16x32_bf16 v[76:79], v[148:151], v[214:217], v[76:79]
	v_mfma_f32_16x16x32_bf16 v[72:75], v[164:167], v[214:217], v[72:75]
	s_setprio 0
	s_setprio 1
	v_mfma_f32_16x16x32_bf16 v[116:119], v[168:171], v[184:187], v[116:119]
	v_mfma_f32_16x16x32_bf16 v[112:115], v[176:179], v[184:187], v[112:115]
	v_mfma_f32_16x16x32_bf16 v[100:103], v[168:171], v[192:195], v[100:103]
	v_mfma_f32_16x16x32_bf16 v[96:99], v[176:179], v[192:195], v[96:99]
	v_mfma_f32_16x16x32_bf16 v[84:87], v[168:171], v[200:203], v[84:87]
	v_mfma_f32_16x16x32_bf16 v[80:83], v[176:179], v[200:203], v[80:83]
	v_mfma_f32_16x16x32_bf16 v[68:71], v[168:171], v[210:213], v[68:71]
	v_mfma_f32_16x16x32_bf16 v[64:67], v[176:179], v[210:213], v[64:67]
	v_mfma_f32_16x16x32_bf16 v[116:119], v[172:175], v[188:191], v[116:119]
	v_mfma_f32_16x16x32_bf16 v[112:115], v[180:183], v[188:191], v[112:115]
	v_mfma_f32_16x16x32_bf16 v[100:103], v[172:175], v[196:199], v[100:103]
	v_mfma_f32_16x16x32_bf16 v[96:99], v[180:183], v[196:199], v[96:99]
	v_mfma_f32_16x16x32_bf16 v[84:87], v[172:175], v[204:207], v[84:87]
	v_mfma_f32_16x16x32_bf16 v[80:83], v[180:183], v[204:207], v[80:83]
	v_mfma_f32_16x16x32_bf16 v[68:71], v[172:175], v[214:217], v[68:71]
	s_barrier
	v_mfma_f32_16x16x32_bf16 v[64:67], v[180:183], v[214:217], v[64:67]
	s_setprio 0
	s_add_i32 s52, s75, s64
	v_lshl_add_u64 v[218:219], s[36:37], 0, v[130:131]
	s_mov_b32 m0, s52
	ds_read_b128 v[184:187], v157 offset:16384
	ds_read_b128 v[188:191], v157 offset:17408
	ds_read_b128 v[192:195], v157 offset:18432
	ds_read_b128 v[196:199], v157 offset:19456
	ds_read_b128 v[200:203], v157 offset:20480
	ds_read_b128 v[204:207], v157 offset:21504
	ds_read_b128 v[210:213], v157 offset:22528
	ds_read_b128 v[214:217], v157 offset:23552
	global_load_lds_dwordx4 v[218:219], off
	s_add_i32 m0, s52, 0x2000
	s_add_u32 s52, s36, 0x40000
	v_lshl_add_u64 v[220:221], s[36:37], 0, v[134:135]
	s_addc_u32 s53, s37, 0
	s_add_i32 s78, s76, s64
	global_load_lds_dwordx4 v[220:221], off
	v_lshl_add_u64 v[222:223], s[52:53], 0, v[130:131]
	s_mov_b32 m0, s78
	v_lshl_add_u64 v[224:225], s[38:39], 0, v[132:133]
	global_load_lds_dwordx4 v[222:223], off
	v_lshl_add_u64 v[222:223], s[52:53], 0, v[134:135]
	s_add_i32 m0, s78, 0x2000
	s_nop 0
	global_load_lds_dwordx4 v[222:223], off
	v_lshl_add_u64 v[222:223], s[38:39], 0, v[128:129]
	s_mov_b32 m0, s67
	s_nop 0
	global_load_lds_dwordx4 v[222:223], off
	s_mov_b32 m0, s68
	s_nop 0
	global_load_lds_dwordx4 v[224:225], off
	s_waitcnt vmcnt(8)
	s_waitcnt lgkmcnt(0)
	s_barrier
; #define PG8_STAGE(bufoff, gbase, voff) do { _Pragma("unroll") for (int _i = 0; _i < 2; ++_i) \
;         __builtin_amdgcn_global_load_lds((const unsigned*)((const char*)(gbase) + (voff)[_i]), (PG8_LAS unsigned*)(lds + (bufoff) + ldsw + _i * 8192), 16, 0, 0); } while (0)
; #define PG8_LDA(dst, b, h) do { _Pragma("unroll") for (int m = 0; m < 4; ++m) _Pragma("unroll") for (int k = 0; k < 2; ++k) dst[m][k] = *(const PG8_LAS bf16x8*)(lds + PG8_SA(b, h) + aoff + m * 2048 + k * 1024); } while (0)
; #define PG8_LDB(dst, b, h) do { _Pragma("unroll") for (int n = 0; n < 2; ++n) _Pragma("unroll") for (int k = 0; k < 2; ++k) dst[n][k] = *(const PG8_LAS bf16x8*)(lds + PG8_SB(b, h) + boff + n * 2048 + k * 1024); } while (0)
; #define PG8_MMA(ai, bj, At, Bt) do { __builtin_amdgcn_s_setprio(1); _Pragma("unroll") for (int m = 0; m < 4; ++m) _Pragma("unroll") for (int n = 0; n < 2; ++n) _Pragma("unroll") for (int k = 0; k < 2; ++k) \
;         acc[ai][bj][m][n] = __builtin_amdgcn_mfma_f32_16x16x32_bf16(Bt[n][k], At[m][k], acc[ai][bj][m][n], 0, 0, 0); __builtin_amdgcn_s_setprio(0); } while (0)
; #define PG8_WAIT_V(n) asm volatile("s_waitcnt vmcnt(" #n ")" ::: "memory")
; #define PG8_WAIT_L(n) asm volatile("s_waitcnt lgkmcnt(" #n ")" ::: "memory")
; #define PG8_BAR __builtin_amdgcn_s_barrier()
; #define PG8_SCHED __builtin_amdgcn_sched_barrier(0)
; template <class Epi, class Sched, bool ALIGN_EPI = false, bool SP2 = false>
; __device__ __forceinline__ void gemm_phase(PG8_LAS unsigned char* lds, const Gemm g, const Sched& S, const Epi& E) {
;     ...
;             PG8_WAIT_V(8); PG8_WAIT_L(0); PG8_BAR; PG8_MMA(1, 0, At, B0); PG8_MMA(1, 1, At, B1); PG8_BAR; PG8_SCHED;
;             PG8_LDB(B0, 1, 0); PG8_LDB(B1, 1, 1); PG8_SCHED; PG8_LDA(At, 1, 0); PG8_STAGE(PG8_SA(0, 1), a2 + hstep, voffA);
;             PG8_WAIT_V(8); PG8_WAIT_L(0); PG8_BAR; PG8_MMA(0, 0, At, B0); PG8_MMA(0, 1, At, B1); PG8_BAR; PG8_SCHED;
;             PG8_LDA(At, 1, 1); PG8_STAGE(PG8_SB(1, 0), b3, voffB); PG8_STAGE(PG8_SB(1, 1), b3 + hstep, voffB); PG8_STAGE(PG8_SA(1, 0), a3, voffA);
	s_setprio 1
	s_waitcnt lgkmcnt(0)
	v_mfma_f32_16x16x32_bf16 v[60:63], v[144:147], v[184:187], v[60:63]
	v_mfma_f32_16x16x32_bf16 v[56:59], v[160:163], v[184:187], v[56:59]
	v_mfma_f32_16x16x32_bf16 v[44:47], v[144:147], v[192:195], v[44:47]
	v_mfma_f32_16x16x32_bf16 v[40:43], v[160:163], v[192:195], v[40:43]
	v_mfma_f32_16x16x32_bf16 v[28:31], v[144:147], v[200:203], v[28:31]
	v_mfma_f32_16x16x32_bf16 v[24:27], v[160:163], v[200:203], v[24:27]
	v_mfma_f32_16x16x32_bf16 v[12:15], v[144:147], v[210:213], v[12:15]
	v_mfma_f32_16x16x32_bf16 v[8:11], v[160:163], v[210:213], v[8:11]
	v_mfma_f32_16x16x32_bf16 v[60:63], v[148:151], v[188:191], v[60:63]
	v_mfma_f32_16x16x32_bf16 v[56:59], v[164:167], v[188:191], v[56:59]
	v_mfma_f32_16x16x32_bf16 v[44:47], v[148:151], v[196:199], v[44:47]
	v_mfma_f32_16x16x32_bf16 v[40:43], v[164:167], v[196:199], v[40:43]
	v_mfma_f32_16x16x32_bf16 v[28:31], v[148:151], v[204:207], v[28:31]
	v_mfma_f32_16x16x32_bf16 v[24:27], v[164:167], v[204:207], v[24:27]
	v_mfma_f32_16x16x32_bf16 v[12:15], v[148:151], v[214:217], v[12:15]
	v_mfma_f32_16x16x32_bf16 v[8:11], v[164:167], v[214:217], v[8:11]
	s_setprio 0
	s_setprio 1
	v_mfma_f32_16x16x32_bf16 v[52:55], v[168:171], v[184:187], v[52:55]
	v_mfma_f32_16x16x32_bf16 v[48:51], v[176:179], v[184:187], v[48:51]
	v_mfma_f32_16x16x32_bf16 v[36:39], v[168:171], v[192:195], v[36:39]
	v_mfma_f32_16x16x32_bf16 v[32:35], v[176:179], v[192:195], v[32:35]
	v_mfma_f32_16x16x32_bf16 v[20:23], v[168:171], v[200:203], v[20:23]
	v_mfma_f32_16x16x32_bf16 v[16:19], v[176:179], v[200:203], v[16:19]
	v_mfma_f32_16x16x32_bf16 v[4:7], v[168:171], v[210:213], v[4:7]
	v_mfma_f32_16x16x32_bf16 v[0:3], v[176:179], v[210:213], v[0:3]
	v_mfma_f32_16x16x32_bf16 v[52:55], v[172:175], v[188:191], v[52:55]
	v_mfma_f32_16x16x32_bf16 v[48:51], v[180:183], v[188:191], v[48:51]
	v_mfma_f32_16x16x32_bf16 v[36:39], v[172:175], v[196:199], v[36:39]
	v_mfma_f32_16x16x32_bf16 v[32:35], v[180:183], v[196:199], v[32:35]
	v_mfma_f32_16x16x32_bf16 v[20:23], v[172:175], v[204:207], v[20:23]
	v_mfma_f32_16x16x32_bf16 v[16:19], v[180:183], v[204:207], v[16:19]
	v_mfma_f32_16x16x32_bf16 v[4:7], v[172:175], v[214:217], v[4:7]
	s_barrier
	v_mfma_f32_16x16x32_bf16 v[0:3], v[180:183], v[214:217], v[0:3]
	s_setprio 0
	s_add_i32 s52, 0, 0x18000
	v_add_u32_e32 v159, s52, v153
	s_add_i32 s53, 0, 0x1c000
	ds_read_b128 v[144:147], v159
	ds_read_b128 v[148:151], v159 offset:1024
	ds_read_b128 v[160:163], v159 offset:2048
	ds_read_b128 v[164:167], v159 offset:3072
	v_add_u32_e32 v159, s53, v153
	ds_read_b128 v[168:171], v159
	ds_read_b128 v[172:175], v159 offset:1024
	ds_read_b128 v[176:179], v159 offset:2048
	ds_read_b128 v[180:183], v159 offset:3072
	s_add_u32 s38, s38, 0x40000
	s_addc_u32 s39, s39, 0
	s_mov_b32 m0, s69
	v_lshl_add_u64 v[226:227], s[38:39], 0, v[128:129]
	ds_read_b128 v[184:187], v157 offset:32768
	ds_read_b128 v[188:191], v157 offset:33792
	ds_read_b128 v[192:195], v157 offset:34816
	ds_read_b128 v[196:199], v157 offset:35840
	ds_read_b128 v[200:203], v157 offset:36864
	ds_read_b128 v[204:207], v157 offset:37888
	ds_read_b128 v[210:213], v157 offset:38912
	ds_read_b128 v[214:217], v157 offset:39936
	global_load_lds_dwordx4 v[226:227], off
	v_lshl_add_u64 v[226:227], s[38:39], 0, v[132:133]
	s_mov_b32 m0, s70
	s_nop 0
	global_load_lds_dwordx4 v[226:227], off
	s_waitcnt vmcnt(8)
	s_waitcnt lgkmcnt(0)
	s_barrier
	s_setprio 1
	s_waitcnt lgkmcnt(0)
	v_mfma_f32_16x16x32_bf16 v[124:127], v[144:147], v[184:187], v[124:127]
	v_mfma_f32_16x16x32_bf16 v[120:123], v[160:163], v[184:187], v[120:123]
	v_mfma_f32_16x16x32_bf16 v[108:111], v[144:147], v[192:195], v[108:111]
	v_mfma_f32_16x16x32_bf16 v[104:107], v[160:163], v[192:195], v[104:107]
	v_mfma_f32_16x16x32_bf16 v[92:95], v[144:147], v[200:203], v[92:95]
	v_mfma_f32_16x16x32_bf16 v[88:91], v[160:163], v[200:203], v[88:91]
	v_mfma_f32_16x16x32_bf16 v[76:79], v[144:147], v[210:213], v[76:79]
	v_mfma_f32_16x16x32_bf16 v[72:75], v[160:163], v[210:213], v[72:75]
	v_mfma_f32_16x16x32_bf16 v[124:127], v[148:151], v[188:191], v[124:127]
	v_mfma_f32_16x16x32_bf16 v[120:123], v[164:167], v[188:191], v[120:123]
	v_mfma_f32_16x16x32_bf16 v[108:111], v[148:151], v[196:199], v[108:111]
	v_mfma_f32_16x16x32_bf16 v[104:107], v[164:167], v[196:199], v[104:107]
	v_mfma_f32_16x16x32_bf16 v[92:95], v[148:151], v[204:207], v[92:95]
	v_mfma_f32_16x16x32_bf16 v[88:91], v[164:167], v[204:207], v[88:91]
	v_mfma_f32_16x16x32_bf16 v[76:79], v[148:151], v[214:217], v[76:79]
	v_mfma_f32_16x16x32_bf16 v[72:75], v[164:167], v[214:217], v[72:75]
	s_setprio 0
	s_setprio 1
	v_mfma_f32_16x16x32_bf16 v[116:119], v[168:171], v[184:187], v[116:119]
	v_mfma_f32_16x16x32_bf16 v[112:115], v[176:179], v[184:187], v[112:115]
	v_mfma_f32_16x16x32_bf16 v[100:103], v[168:171], v[192:195], v[100:103]
	v_mfma_f32_16x16x32_bf16 v[96:99], v[176:179], v[192:195], v[96:99]
	v_mfma_f32_16x16x32_bf16 v[84:87], v[168:171], v[200:203], v[84:87]
	v_mfma_f32_16x16x32_bf16 v[80:83], v[176:179], v[200:203], v[80:83]
	v_mfma_f32_16x16x32_bf16 v[68:71], v[168:171], v[210:213], v[68:71]
	v_mfma_f32_16x16x32_bf16 v[64:67], v[176:179], v[210:213], v[64:67]
	v_mfma_f32_16x16x32_bf16 v[116:119], v[172:175], v[188:191], v[116:119]
	v_mfma_f32_16x16x32_bf16 v[112:115], v[180:183], v[188:191], v[112:115]
	v_mfma_f32_16x16x32_bf16 v[100:103], v[172:175], v[196:199], v[100:103]
	v_mfma_f32_16x16x32_bf16 v[96:99], v[180:183], v[196:199], v[96:99]
	v_mfma_f32_16x16x32_bf16 v[84:87], v[172:175], v[204:207], v[84:87]
	v_mfma_f32_16x16x32_bf16 v[80:83], v[180:183], v[204:207], v[80:83]
	v_mfma_f32_16x16x32_bf16 v[68:71], v[172:175], v[214:217], v[68:71]
	s_barrier
; #define PG8_STAGE(bufoff, gbase, voff) do { _Pragma("unroll") for (int _i = 0; _i < 2; ++_i) \
;         __builtin_amdgcn_global_load_lds((const unsigned*)((const char*)(gbase) + (voff)[_i]), (PG8_LAS unsigned*)(lds + (bufoff) + ldsw + _i * 8192), 16, 0, 0); } while (0)
; #define PG8_LDA(dst, b, h) do { _Pragma("unroll") for (int m = 0; m < 4; ++m) _Pragma("unroll") for (int k = 0; k < 2; ++k) dst[m][k] = *(const PG8_LAS bf16x8*)(lds + PG8_SA(b, h) + aoff + m * 2048 + k * 1024); } while (0)
; #define PG8_MMA(ai, bj, At, Bt) do { __builtin_amdgcn_s_setprio(1); _Pragma("unroll") for (int m = 0; m < 4; ++m) _Pragma("unroll") for (int n = 0; n < 2; ++n) _Pragma("unroll") for (int k = 0; k < 2; ++k) \
;         acc[ai][bj][m][n] = __builtin_amdgcn_mfma_f32_16x16x32_bf16(Bt[n][k], At[m][k], acc[ai][bj][m][n], 0, 0, 0); __builtin_amdgcn_s_setprio(0); } while (0)
; #define PG8_WAIT_V(n) asm volatile("s_waitcnt vmcnt(" #n ")" ::: "memory")
; #define PG8_WAIT_L(n) asm volatile("s_waitcnt lgkmcnt(" #n ")" ::: "memory")
; #define PG8_BAR __builtin_amdgcn_s_barrier()
; #define PG8_SCHED __builtin_amdgcn_sched_barrier(0)
; template <class Epi, class Sched, bool ALIGN_EPI = false, bool SP2 = false>
; __device__ __forceinline__ void gemm_phase(PG8_LAS unsigned char* lds, const Gemm g, const Sched& S, const Epi& E) {
;     ...
;             PG8_WAIT_V(8); PG8_WAIT_L(0); PG8_BAR; PG8_MMA(0, 0, At, B0); PG8_MMA(0, 1, At, B1); PG8_BAR; PG8_SCHED;
;             PG8_LDA(At, 1, 1); PG8_STAGE(PG8_SB(1, 0), b3, voffB); PG8_STAGE(PG8_SB(1, 1), b3 + hstep, voffB); PG8_STAGE(PG8_SA(1, 0), a3, voffA);
;             PG8_WAIT_V(8); PG8_WAIT_L(0); PG8_BAR; PG8_MMA(1, 0, At, B0); PG8_MMA(1, 1, At, B1); PG8_BAR; PG8_SCHED;
;     ...
;         if constexpr (ALIGN_EPI) { if (wr == 0) PG8_BAR; }
	v_mfma_f32_16x16x32_bf16 v[64:67], v[180:183], v[214:217], v[64:67]
	s_setprio 0
	s_add_i32 s38, s52, s64
	v_lshl_add_u64 v[218:219], v[218:219], 0, s[16:17]
	s_mov_b32 m0, s38
	ds_read_b128 v[184:187], v157 offset:49152
	ds_read_b128 v[188:191], v157 offset:50176
	ds_read_b128 v[192:195], v157 offset:51200
	ds_read_b128 v[196:199], v157 offset:52224
	ds_read_b128 v[200:203], v157 offset:53248
	ds_read_b128 v[204:207], v157 offset:54272
	ds_read_b128 v[210:213], v157 offset:55296
	ds_read_b128 v[214:217], v157 offset:56320
	global_load_lds_dwordx4 v[218:219], off
	s_add_i32 m0, s38, 0x2000
	s_add_u32 s36, s36, 0x40080
	v_lshl_add_u64 v[218:219], v[220:221], 0, s[16:17]
	s_addc_u32 s37, s37, 0
	s_add_i32 s38, s53, s64
	global_load_lds_dwordx4 v[218:219], off
	v_lshl_add_u64 v[218:219], s[36:37], 0, v[130:131]
	s_mov_b32 m0, s38
	s_nop 0
	global_load_lds_dwordx4 v[218:219], off
	v_lshl_add_u64 v[218:219], s[36:37], 0, v[134:135]
	s_add_i32 m0, s38, 0x2000
	s_nop 0
	global_load_lds_dwordx4 v[218:219], off
	v_lshl_add_u64 v[218:219], v[222:223], 0, s[16:17]
	s_mov_b32 m0, s72
	s_nop 0
	global_load_lds_dwordx4 v[218:219], off
	v_lshl_add_u64 v[218:219], v[224:225], 0, s[16:17]
	s_mov_b32 m0, s73
	s_nop 0
	global_load_lds_dwordx4 v[218:219], off
	s_waitcnt vmcnt(8)
	s_waitcnt lgkmcnt(0)
	s_barrier
	s_setprio 1
	s_waitcnt lgkmcnt(0)
	v_mfma_f32_16x16x32_bf16 v[60:63], v[144:147], v[184:187], v[60:63]
	v_mfma_f32_16x16x32_bf16 v[56:59], v[160:163], v[184:187], v[56:59]
	v_mfma_f32_16x16x32_bf16 v[44:47], v[144:147], v[192:195], v[44:47]
	v_mfma_f32_16x16x32_bf16 v[40:43], v[160:163], v[192:195], v[40:43]
	v_mfma_f32_16x16x32_bf16 v[28:31], v[144:147], v[200:203], v[28:31]
	v_mfma_f32_16x16x32_bf16 v[24:27], v[160:163], v[200:203], v[24:27]
	v_mfma_f32_16x16x32_bf16 v[12:15], v[144:147], v[210:213], v[12:15]
	v_mfma_f32_16x16x32_bf16 v[8:11], v[160:163], v[210:213], v[8:11]
	v_mfma_f32_16x16x32_bf16 v[60:63], v[148:151], v[188:191], v[60:63]
	v_mfma_f32_16x16x32_bf16 v[56:59], v[164:167], v[188:191], v[56:59]
	v_mfma_f32_16x16x32_bf16 v[44:47], v[148:151], v[196:199], v[44:47]
	v_mfma_f32_16x16x32_bf16 v[40:43], v[164:167], v[196:199], v[40:43]
	v_mfma_f32_16x16x32_bf16 v[28:31], v[148:151], v[204:207], v[28:31]
	v_mfma_f32_16x16x32_bf16 v[24:27], v[164:167], v[204:207], v[24:27]
	v_mfma_f32_16x16x32_bf16 v[12:15], v[148:151], v[214:217], v[12:15]
	v_mfma_f32_16x16x32_bf16 v[8:11], v[164:167], v[214:217], v[8:11]
	s_setprio 0
	s_setprio 1
	v_mfma_f32_16x16x32_bf16 v[52:55], v[168:171], v[184:187], v[52:55]
	v_mfma_f32_16x16x32_bf16 v[48:51], v[176:179], v[184:187], v[48:51]
	v_mfma_f32_16x16x32_bf16 v[36:39], v[168:171], v[192:195], v[36:39]
	v_mfma_f32_16x16x32_bf16 v[32:35], v[176:179], v[192:195], v[32:35]
	v_mfma_f32_16x16x32_bf16 v[20:23], v[168:171], v[200:203], v[20:23]
	v_mfma_f32_16x16x32_bf16 v[16:19], v[176:179], v[200:203], v[16:19]
	v_mfma_f32_16x16x32_bf16 v[4:7], v[168:171], v[210:213], v[4:7]
	v_mfma_f32_16x16x32_bf16 v[0:3], v[176:179], v[210:213], v[0:3]
	v_mfma_f32_16x16x32_bf16 v[52:55], v[172:175], v[188:191], v[52:55]
	v_mfma_f32_16x16x32_bf16 v[48:51], v[180:183], v[188:191], v[48:51]
	v_mfma_f32_16x16x32_bf16 v[36:39], v[172:175], v[196:199], v[36:39]
	v_mfma_f32_16x16x32_bf16 v[32:35], v[180:183], v[196:199], v[32:35]
	v_mfma_f32_16x16x32_bf16 v[20:23], v[172:175], v[204:207], v[20:23]
	v_mfma_f32_16x16x32_bf16 v[16:19], v[180:183], v[204:207], v[16:19]
	v_mfma_f32_16x16x32_bf16 v[4:7], v[172:175], v[214:217], v[4:7]
	s_barrier
	v_mfma_f32_16x16x32_bf16 v[0:3], v[180:183], v[214:217], v[0:3]
	s_setprio 0
	s_add_i32 s84, s84, 2
	s_add_u32 s34, s34, 0x100
	s_addc_u32 s35, s35, 0
	s_add_u32 s82, s82, 0x100
	s_addc_u32 s83, s83, 0
	s_cmp_gt_u32 s84, 13
	s_cbranch_scc0 .LBB0_1271
	s_cmp_eq_u32 s101, 0
	s_cbranch_scc1 .Lp11_war_ok
	s_mov_b64 exec, 1
	s_lshl_b32 s98, s33, 8
	s_add_u32 s98, s46, s98
	s_addc_u32 s99, s47, 0
	v_mov_b32_e32 v176, 0x10000
	s_mov_b32 s97, 0
.Lp11_war_poll:
	global_load_dword v177, v176, s[98:99] sc1
	s_waitcnt vmcnt(0)
	v_readfirstlane_b32 s96, v177
	s_cmp_ge_u32 s96, s101
	s_cbranch_scc1 .Lp11_war_done
	s_sleep 1
	s_add_i32 s97, s97, 1
	s_cmp_lt_u32 s97, 20000
	s_cbranch_scc1 .Lp11_war_poll
.Lp11_war_done:
	s_mov_b32 s101, 0
	s_mov_b64 exec, -1
.Lp11_war_ok:
	s_and_b64 vcc, exec, s[18:19]
	s_cbranch_vccz .LBB0_1274
	s_barrier
; __device__ __forceinline__ unsigned cvt_pk_bf16(float lo, float hi) { cvf32x2_t v = {lo, hi}; cvbf16x2_t b = __builtin_convertvector(v, cvbf16x2_t); return __builtin_bit_cast(unsigned, b); }
; __device__ __forceinline__ float fsilu(float x) { return x * fsigm(x); }
; __device__ __forceinline__ float row_rs(const float* ssq, int row) { return ssq ? rsqrtf(ssq[row] * (1.f / 1024.f) + RMS_EPS) : 1.f; }
;     __device__ __forceinline__ void operator()(const f32x4 (&acc)[2][2][4][2], const Unit& u, int wr, int wc, int fr, int fq) const {
;         const int row0 = u.pm * BM + wr * 64 + fr, col0 = u.pn * HALF + wc * 32 + 8 * fq;
; #pragma unroll
;         for (int ai = 0; ai < 2; ++ai)
; #pragma unroll
;             for (int m = 0; m < 4; ++m) { const int row = row0 + ai * HALF + m * 16; const float rs = row_rs(ssq, row);
;                 u32x4 w; unsigned pk[4];
; #pragma unroll
;                 for (int n = 0; n < 2; ++n) { const f32x4 g = acc[ai][0][m][n] * rs, up = acc[ai][1][m][n] * rs;
;                     pk[2 * n] = cvt_pk_bf16(fsilu(g[0]) * up[0], fsilu(g[1]) * up[1]); pk[2 * n + 1] = cvt_pk_bf16(fsilu(g[2]) * up[2], fsilu(g[3]) * up[3]); }
;                 w.x = pk[0]; w.y = pk[1]; w.z = pk[2]; w.w = pk[3];
;                 st_wt16(H + (size_t)row * ldh + col0, w); }
.LBB0_1274:
	v_lshl_add_u32 v144, s6, 8, v152
	v_ashrrev_i32_e32 v145, 31, v144
	v_lshl_add_u64 v[150:151], v[144:145], 2, s[12:13]
	global_load_dword v145, v[150:151], off
	v_or_b32_e32 v162, 16, v144
	v_ashrrev_i32_e32 v163, 31, v162
	v_lshl_add_u64 v[164:165], v[162:163], 2, s[12:13]
	v_lshl_or_b32 v148, s7, 7, v154
	v_mov_b64_e32 v[146:147], s[56:57]
	v_ashrrev_i32_e32 v149, 31, v148
	v_mad_i64_i32 v[160:161], s[6:7], v144, s79, v[146:147]
	v_lshlrev_b64 v[148:149], 1, v[148:149]
	v_lshl_add_u64 v[160:161], v[160:161], 0, v[148:149]
	s_waitcnt vmcnt(0)
	v_fmamk_f32 v145, v145, 0x3a800000, v158
	v_mul_f32_e32 v159, 0x4b800000, v145
	v_cmp_gt_f32_e32 vcc, s77, v145
	s_nop 1
	v_cndmask_b32_e32 v145, v145, v159, vcc
	v_rsq_f32_e32 v145, v145
	s_nop 0
	v_mul_f32_e32 v159, 0x45800000, v145
	v_cndmask_b32_e32 v166, v145, v159, vcc
	v_pk_mul_f32 v[126:127], v[126:127], v[166:167] op_sel_hi:[1,0]
	v_pk_mul_f32 v[124:125], v[124:125], v[166:167] op_sel_hi:[1,0]
	v_pk_mul_f32 v[122:123], v[122:123], v[166:167] op_sel_hi:[1,0]
	v_pk_mul_f32 v[120:121], v[120:121], v[166:167] op_sel_hi:[1,0]
	v_pk_mul_f32 v[118:119], v[118:119], v[166:167] op_sel_hi:[1,0]
	v_pk_mul_f32 v[116:117], v[116:117], v[166:167] op_sel_hi:[1,0]
	v_pk_mul_f32 v[114:115], v[114:115], v[166:167] op_sel_hi:[1,0]
	v_pk_mul_f32 v[112:113], v[112:113], v[166:167] op_sel_hi:[1,0]
	v_mul_f32_e32 v145, 0xbfb8aa3b, v124
	v_mul_f32_e32 v159, 0xbfb8aa3b, v125
	v_mul_f32_e32 v163, 0xbfb8aa3b, v126
	v_mul_f32_e32 v166, 0xbfb8aa3b, v127
	v_mul_f32_e32 v167, 0xbfb8aa3b, v120
	v_mul_f32_e32 v168, 0xbfb8aa3b, v121
	v_mul_f32_e32 v169, 0xbfb8aa3b, v122
	v_mul_f32_e32 v170, 0xbfb8aa3b, v123
	v_exp_f32_e32 v145, v145
	v_exp_f32_e32 v159, v159
	v_exp_f32_e32 v163, v163
	v_exp_f32_e32 v166, v166
	v_exp_f32_e32 v167, v167
	v_exp_f32_e32 v168, v168
	v_exp_f32_e32 v169, v169
	v_exp_f32_e32 v170, v170
	v_add_f32_e32 v145, 1.0, v145
	v_add_f32_e32 v159, 1.0, v159
	v_add_f32_e32 v163, 1.0, v163
	v_add_f32_e32 v171, 1.0, v166
	v_add_f32_e32 v172, 1.0, v167
	v_add_f32_e32 v173, 1.0, v168
	v_add_f32_e32 v174, 1.0, v169
	v_add_f32_e32 v175, 1.0, v170
	v_rcp_f32_e32 v166, v145
	v_rcp_f32_e32 v167, v159
	v_rcp_f32_e32 v168, v163
	v_rcp_f32_e32 v169, v171
	v_rcp_f32_e32 v170, v172
	v_rcp_f32_e32 v171, v173
	v_rcp_f32_e32 v172, v174
	v_rcp_f32_e32 v173, v175
	v_pk_mul_f32 v[124:125], v[124:125], v[166:167]
	v_pk_mul_f32 v[126:127], v[126:127], v[168:169]
	v_pk_mul_f32 v[120:121], v[120:121], v[170:171]
	v_pk_mul_f32 v[122:123], v[122:123], v[172:173]
	v_pk_mul_f32 v[116:117], v[116:117], v[124:125]
	v_pk_mul_f32 v[118:119], v[118:119], v[126:127]
	v_pk_mul_f32 v[120:121], v[112:113], v[120:121]
	v_pk_mul_f32 v[122:123], v[114:115], v[122:123]
	v_cvt_pk_bf16_f32 v112, v116, v117
	v_cvt_pk_bf16_f32 v113, v118, v119
	v_cvt_pk_bf16_f32 v114, v120, v121
	v_cvt_pk_bf16_f32 v115, v122, v123
	global_store_dwordx4 v[160:161], v[112:115], off
	global_load_dword v113, v[164:165], off
	s_nop 0
	v_or_b32_e32 v112, 32, v144
	v_mad_i64_i32 v[114:115], s[6:7], v162, s79, v[146:147]
	v_lshl_add_u64 v[114:115], v[114:115], 0, v[148:149]
	s_waitcnt vmcnt(0)
	v_fmamk_f32 v113, v113, 0x3a800000, v158
	v_mul_f32_e32 v116, 0x4b800000, v113
	v_cmp_gt_f32_e32 vcc, s77, v113
	s_nop 1
	v_cndmask_b32_e32 v113, v113, v116, vcc
	v_rsq_f32_e32 v118, v113
	v_ashrrev_i32_e32 v113, 31, v112
	v_lshl_add_u64 v[116:117], v[112:113], 2, s[12:13]
	v_mul_f32_e32 v113, 0x45800000, v118
	v_cndmask_b32_e32 v118, v118, v113, vcc
	v_pk_mul_f32 v[110:111], v[110:111], v[118:119] op_sel_hi:[1,0]
	v_pk_mul_f32 v[108:109], v[108:109], v[118:119] op_sel_hi:[1,0]
	v_pk_mul_f32 v[106:107], v[106:107], v[118:119] op_sel_hi:[1,0]
	v_pk_mul_f32 v[104:105], v[104:105], v[118:119] op_sel_hi:[1,0]
	v_pk_mul_f32 v[102:103], v[102:103], v[118:119] op_sel_hi:[1,0]
	v_pk_mul_f32 v[100:101], v[100:101], v[118:119] op_sel_hi:[1,0]
	v_pk_mul_f32 v[98:99], v[98:99], v[118:119] op_sel_hi:[1,0]
	v_pk_mul_f32 v[96:97], v[96:97], v[118:119] op_sel_hi:[1,0]
	v_mul_f32_e32 v113, 0xbfb8aa3b, v108
	v_mul_f32_e32 v118, 0xbfb8aa3b, v109
	v_mul_f32_e32 v119, 0xbfb8aa3b, v110
	v_mul_f32_e32 v120, 0xbfb8aa3b, v111
	v_mul_f32_e32 v121, 0xbfb8aa3b, v104
	v_mul_f32_e32 v122, 0xbfb8aa3b, v105
	v_mul_f32_e32 v123, 0xbfb8aa3b, v106
	v_mul_f32_e32 v124, 0xbfb8aa3b, v107
	v_exp_f32_e32 v113, v113
	v_exp_f32_e32 v118, v118
	v_exp_f32_e32 v119, v119
	v_exp_f32_e32 v120, v120
	v_exp_f32_e32 v121, v121
	v_exp_f32_e32 v122, v122
	v_exp_f32_e32 v123, v123
	v_exp_f32_e32 v124, v124
	v_add_f32_e32 v113, 1.0, v113
	v_add_f32_e32 v125, 1.0, v118
	v_add_f32_e32 v126, 1.0, v119
	v_add_f32_e32 v127, 1.0, v120
	v_add_f32_e32 v145, 1.0, v121
	v_add_f32_e32 v159, 1.0, v122
	v_add_f32_e32 v160, 1.0, v123
	v_add_f32_e32 v161, 1.0, v124
	v_rcp_f32_e32 v118, v113
	v_rcp_f32_e32 v119, v125
	v_rcp_f32_e32 v120, v126
	v_rcp_f32_e32 v121, v127
	v_rcp_f32_e32 v122, v145
	v_rcp_f32_e32 v123, v159
	v_rcp_f32_e32 v124, v160
	v_rcp_f32_e32 v125, v161
	v_pk_mul_f32 v[108:109], v[108:109], v[118:119]
	v_pk_mul_f32 v[110:111], v[110:111], v[120:121]
	v_pk_mul_f32 v[104:105], v[104:105], v[122:123]
	v_pk_mul_f32 v[106:107], v[106:107], v[124:125]
	v_pk_mul_f32 v[100:101], v[100:101], v[108:109]
	v_pk_mul_f32 v[102:103], v[102:103], v[110:111]
	v_pk_mul_f32 v[104:105], v[96:97], v[104:105]
	v_pk_mul_f32 v[106:107], v[98:99], v[106:107]
	v_cvt_pk_bf16_f32 v96, v100, v101
	v_cvt_pk_bf16_f32 v97, v102, v103
	v_cvt_pk_bf16_f32 v98, v104, v105
	v_cvt_pk_bf16_f32 v99, v106, v107
	global_store_dwordx4 v[114:115], v[96:99], off
	global_load_dword v97, v[116:117], off
	s_nop 0
	v_or_b32_e32 v96, 48, v144
	v_mad_i64_i32 v[98:99], s[6:7], v112, s79, v[146:147]
	v_lshl_add_u64 v[98:99], v[98:99], 0, v[148:149]
	s_waitcnt vmcnt(0)
; __device__ __forceinline__ unsigned cvt_pk_bf16(float lo, float hi) { cvf32x2_t v = {lo, hi}; cvbf16x2_t b = __builtin_convertvector(v, cvbf16x2_t); return __builtin_bit_cast(unsigned, b); }
; __device__ __forceinline__ float fsigm(float x) { return __builtin_amdgcn_rcpf(1.f + __expf(-x)); }
; __device__ __forceinline__ float fsilu(float x) { return x * fsigm(x); }
; __device__ __forceinline__ float row_rs(const float* ssq, int row) { return ssq ? rsqrtf(ssq[row] * (1.f / 1024.f) + RMS_EPS) : 1.f; }
;     __device__ __forceinline__ void operator()(const f32x4 (&acc)[2][2][4][2], const Unit& u, int wr, int wc, int fr, int fq) const {
;     ...
;             for (int m = 0; m < 4; ++m) { const int row = row0 + ai * HALF + m * 16; const float rs = row_rs(ssq, row);
;                 u32x4 w; unsigned pk[4];
; #pragma unroll
;                 for (int n = 0; n < 2; ++n) { const f32x4 g = acc[ai][0][m][n] * rs, up = acc[ai][1][m][n] * rs;
;                     pk[2 * n] = cvt_pk_bf16(fsilu(g[0]) * up[0], fsilu(g[1]) * up[1]); pk[2 * n + 1] = cvt_pk_bf16(fsilu(g[2]) * up[2], fsilu(g[3]) * up[3]); }
;                 w.x = pk[0]; w.y = pk[1]; w.z = pk[2]; w.w = pk[3];
;                 st_wt16(H + (size_t)row * ldh + col0, w); }
	v_fmamk_f32 v97, v97, 0x3a800000, v158
	v_mul_f32_e32 v100, 0x4b800000, v97
	v_cmp_gt_f32_e32 vcc, s77, v97
	s_nop 1
	v_cndmask_b32_e32 v97, v97, v100, vcc
	v_rsq_f32_e32 v102, v97
	v_ashrrev_i32_e32 v97, 31, v96
	v_lshl_add_u64 v[100:101], v[96:97], 2, s[12:13]
	v_mul_f32_e32 v97, 0x45800000, v102
	v_cndmask_b32_e32 v102, v102, v97, vcc
	v_pk_mul_f32 v[94:95], v[94:95], v[102:103] op_sel_hi:[1,0]
	v_pk_mul_f32 v[92:93], v[92:93], v[102:103] op_sel_hi:[1,0]
	v_pk_mul_f32 v[90:91], v[90:91], v[102:103] op_sel_hi:[1,0]
	v_pk_mul_f32 v[88:89], v[88:89], v[102:103] op_sel_hi:[1,0]
	v_pk_mul_f32 v[86:87], v[86:87], v[102:103] op_sel_hi:[1,0]
	v_pk_mul_f32 v[84:85], v[84:85], v[102:103] op_sel_hi:[1,0]
	v_pk_mul_f32 v[82:83], v[82:83], v[102:103] op_sel_hi:[1,0]
	v_pk_mul_f32 v[80:81], v[80:81], v[102:103] op_sel_hi:[1,0]
	v_mul_f32_e32 v97, 0xbfb8aa3b, v92
	v_mul_f32_e32 v102, 0xbfb8aa3b, v93
	v_mul_f32_e32 v103, 0xbfb8aa3b, v94
	v_mul_f32_e32 v104, 0xbfb8aa3b, v95
	v_mul_f32_e32 v105, 0xbfb8aa3b, v88
	v_mul_f32_e32 v106, 0xbfb8aa3b, v89
	v_mul_f32_e32 v107, 0xbfb8aa3b, v90
	v_mul_f32_e32 v108, 0xbfb8aa3b, v91
	v_exp_f32_e32 v97, v97
	v_exp_f32_e32 v102, v102
	v_exp_f32_e32 v103, v103
	v_exp_f32_e32 v104, v104
	v_exp_f32_e32 v105, v105
	v_exp_f32_e32 v106, v106
	v_exp_f32_e32 v107, v107
	v_exp_f32_e32 v108, v108
	v_add_f32_e32 v97, 1.0, v97
	v_add_f32_e32 v109, 1.0, v102
	v_add_f32_e32 v110, 1.0, v103
	v_add_f32_e32 v111, 1.0, v104
	v_add_f32_e32 v112, 1.0, v105
	v_add_f32_e32 v113, 1.0, v106
	v_add_f32_e32 v114, 1.0, v107
	v_add_f32_e32 v115, 1.0, v108
	v_rcp_f32_e32 v102, v97
	v_rcp_f32_e32 v103, v109
	v_rcp_f32_e32 v104, v110
	v_rcp_f32_e32 v105, v111
	v_rcp_f32_e32 v106, v112
	v_rcp_f32_e32 v107, v113
	v_rcp_f32_e32 v108, v114
	v_rcp_f32_e32 v109, v115
	v_pk_mul_f32 v[92:93], v[92:93], v[102:103]
	v_pk_mul_f32 v[94:95], v[94:95], v[104:105]
	v_pk_mul_f32 v[88:89], v[88:89], v[106:107]
	v_pk_mul_f32 v[90:91], v[90:91], v[108:109]
	v_pk_mul_f32 v[84:85], v[84:85], v[92:93]
	v_pk_mul_f32 v[86:87], v[86:87], v[94:95]
	v_pk_mul_f32 v[88:89], v[80:81], v[88:89]
	v_pk_mul_f32 v[90:91], v[82:83], v[90:91]
	v_cvt_pk_bf16_f32 v80, v84, v85
	v_cvt_pk_bf16_f32 v81, v86, v87
	v_cvt_pk_bf16_f32 v82, v88, v89
	v_cvt_pk_bf16_f32 v83, v90, v91
	global_store_dwordx4 v[98:99], v[80:83], off
	global_load_dword v80, v[100:101], off
	s_waitcnt vmcnt(0)
	v_fmamk_f32 v80, v80, 0x3a800000, v158
	v_mul_f32_e32 v81, 0x4b800000, v80
	v_cmp_gt_f32_e32 vcc, s77, v80
	s_nop 1
	v_cndmask_b32_e32 v80, v80, v81, vcc
	v_rsq_f32_e32 v82, v80
	v_mad_i64_i32 v[80:81], s[6:7], v96, s79, v[146:147]
	v_lshl_add_u64 v[80:81], v[80:81], 0, v[148:149]
	v_mul_f32_e32 v83, 0x45800000, v82
	v_cndmask_b32_e32 v82, v82, v83, vcc
	v_pk_mul_f32 v[78:79], v[78:79], v[82:83] op_sel_hi:[1,0]
	v_pk_mul_f32 v[76:77], v[76:77], v[82:83] op_sel_hi:[1,0]
	v_pk_mul_f32 v[74:75], v[74:75], v[82:83] op_sel_hi:[1,0]
	v_pk_mul_f32 v[72:73], v[72:73], v[82:83] op_sel_hi:[1,0]
	v_pk_mul_f32 v[70:71], v[70:71], v[82:83] op_sel_hi:[1,0]
	v_pk_mul_f32 v[68:69], v[68:69], v[82:83] op_sel_hi:[1,0]
	v_pk_mul_f32 v[66:67], v[66:67], v[82:83] op_sel_hi:[1,0]
	v_pk_mul_f32 v[64:65], v[64:65], v[82:83] op_sel_hi:[1,0]
	v_mul_f32_e32 v82, 0xbfb8aa3b, v76
	v_mul_f32_e32 v83, 0xbfb8aa3b, v77
	v_mul_f32_e32 v84, 0xbfb8aa3b, v78
	v_mul_f32_e32 v85, 0xbfb8aa3b, v79
	v_mul_f32_e32 v86, 0xbfb8aa3b, v72
	v_mul_f32_e32 v87, 0xbfb8aa3b, v73
	v_mul_f32_e32 v88, 0xbfb8aa3b, v74
	v_mul_f32_e32 v89, 0xbfb8aa3b, v75
	v_exp_f32_e32 v82, v82
	v_exp_f32_e32 v83, v83
	v_exp_f32_e32 v84, v84
	v_exp_f32_e32 v85, v85
	v_exp_f32_e32 v86, v86
	v_exp_f32_e32 v87, v87
	v_exp_f32_e32 v88, v88
	v_exp_f32_e32 v89, v89
	v_add_f32_e32 v82, 1.0, v82
	v_add_f32_e32 v83, 1.0, v83
	v_add_f32_e32 v84, 1.0, v84
	v_add_f32_e32 v85, 1.0, v85
	v_add_f32_e32 v86, 1.0, v86
	v_add_f32_e32 v87, 1.0, v87
	v_add_f32_e32 v88, 1.0, v88
	v_add_f32_e32 v89, 1.0, v89
	v_rcp_f32_e32 v82, v82
	v_rcp_f32_e32 v83, v83
	v_rcp_f32_e32 v84, v84
	v_rcp_f32_e32 v85, v85
	v_rcp_f32_e32 v86, v86
	v_rcp_f32_e32 v87, v87
	v_rcp_f32_e32 v88, v88
	v_rcp_f32_e32 v89, v89
	v_pk_mul_f32 v[76:77], v[76:77], v[82:83]
	v_pk_mul_f32 v[78:79], v[78:79], v[84:85]
	v_pk_mul_f32 v[72:73], v[72:73], v[86:87]
	v_pk_mul_f32 v[74:75], v[74:75], v[88:89]
	v_pk_mul_f32 v[68:69], v[68:69], v[76:77]
	v_pk_mul_f32 v[70:71], v[70:71], v[78:79]
	v_pk_mul_f32 v[72:73], v[64:65], v[72:73]
	v_pk_mul_f32 v[74:75], v[66:67], v[74:75]
	v_cvt_pk_bf16_f32 v64, v68, v69
	v_cvt_pk_bf16_f32 v65, v70, v71
	v_cvt_pk_bf16_f32 v66, v72, v73
	v_cvt_pk_bf16_f32 v67, v74, v75
	global_store_dwordx4 v[80:81], v[64:67], off
	global_load_dword v64, v[150:151], off offset:512
	s_nop 0
	v_add_u32_e32 v65, 0x80, v144
	s_waitcnt vmcnt(0)
; __device__ __forceinline__ unsigned cvt_pk_bf16(float lo, float hi) { cvf32x2_t v = {lo, hi}; cvbf16x2_t b = __builtin_convertvector(v, cvbf16x2_t); return __builtin_bit_cast(unsigned, b); }
; __device__ __forceinline__ float fsigm(float x) { return __builtin_amdgcn_rcpf(1.f + __expf(-x)); }
; __device__ __forceinline__ float fsilu(float x) { return x * fsigm(x); }
; __device__ __forceinline__ float row_rs(const float* ssq, int row) { return ssq ? rsqrtf(ssq[row] * (1.f / 1024.f) + RMS_EPS) : 1.f; }
;     __device__ __forceinline__ void operator()(const f32x4 (&acc)[2][2][4][2], const Unit& u, int wr, int wc, int fr, int fq) const {
;     ...
;             for (int m = 0; m < 4; ++m) { const int row = row0 + ai * HALF + m * 16; const float rs = row_rs(ssq, row);
;                 u32x4 w; unsigned pk[4];
; #pragma unroll
;                 for (int n = 0; n < 2; ++n) { const f32x4 g = acc[ai][0][m][n] * rs, up = acc[ai][1][m][n] * rs;
;                     pk[2 * n] = cvt_pk_bf16(fsilu(g[0]) * up[0], fsilu(g[1]) * up[1]); pk[2 * n + 1] = cvt_pk_bf16(fsilu(g[2]) * up[2], fsilu(g[3]) * up[3]); }
;                 w.x = pk[0]; w.y = pk[1]; w.z = pk[2]; w.w = pk[3];
;                 st_wt16(H + (size_t)row * ldh + col0, w); }
	v_fmamk_f32 v64, v64, 0x3a800000, v158
	v_mul_f32_e32 v66, 0x4b800000, v64
	v_cmp_gt_f32_e32 vcc, s77, v64
	s_nop 1
	v_cndmask_b32_e32 v64, v64, v66, vcc
	v_rsq_f32_e32 v66, v64
	v_mad_i64_i32 v[64:65], s[6:7], v65, s79, v[146:147]
	v_lshl_add_u64 v[64:65], v[64:65], 0, v[148:149]
	v_mul_f32_e32 v67, 0x45800000, v66
	v_cndmask_b32_e32 v66, v66, v67, vcc
	v_pk_mul_f32 v[62:63], v[62:63], v[66:67] op_sel_hi:[1,0]
	v_pk_mul_f32 v[60:61], v[60:61], v[66:67] op_sel_hi:[1,0]
	v_pk_mul_f32 v[58:59], v[58:59], v[66:67] op_sel_hi:[1,0]
	v_pk_mul_f32 v[56:57], v[56:57], v[66:67] op_sel_hi:[1,0]
	v_pk_mul_f32 v[54:55], v[54:55], v[66:67] op_sel_hi:[1,0]
	v_pk_mul_f32 v[52:53], v[52:53], v[66:67] op_sel_hi:[1,0]
	v_pk_mul_f32 v[50:51], v[50:51], v[66:67] op_sel_hi:[1,0]
	v_pk_mul_f32 v[48:49], v[48:49], v[66:67] op_sel_hi:[1,0]
	v_mul_f32_e32 v66, 0xbfb8aa3b, v60
	v_mul_f32_e32 v67, 0xbfb8aa3b, v61
	v_mul_f32_e32 v68, 0xbfb8aa3b, v62
	v_mul_f32_e32 v69, 0xbfb8aa3b, v63
	v_mul_f32_e32 v70, 0xbfb8aa3b, v56
	v_mul_f32_e32 v71, 0xbfb8aa3b, v57
	v_mul_f32_e32 v72, 0xbfb8aa3b, v58
	v_mul_f32_e32 v73, 0xbfb8aa3b, v59
	v_exp_f32_e32 v66, v66
	v_exp_f32_e32 v67, v67
	v_exp_f32_e32 v68, v68
	v_exp_f32_e32 v69, v69
	v_exp_f32_e32 v70, v70
	v_exp_f32_e32 v71, v71
	v_exp_f32_e32 v72, v72
	v_exp_f32_e32 v73, v73
	v_add_f32_e32 v66, 1.0, v66
	v_add_f32_e32 v67, 1.0, v67
	v_add_f32_e32 v68, 1.0, v68
	v_add_f32_e32 v69, 1.0, v69
	v_add_f32_e32 v70, 1.0, v70
	v_add_f32_e32 v71, 1.0, v71
	v_add_f32_e32 v72, 1.0, v72
	v_add_f32_e32 v73, 1.0, v73
	v_rcp_f32_e32 v66, v66
	v_rcp_f32_e32 v67, v67
	v_rcp_f32_e32 v68, v68
	v_rcp_f32_e32 v69, v69
	v_rcp_f32_e32 v70, v70
	v_rcp_f32_e32 v71, v71
	v_rcp_f32_e32 v72, v72
	v_rcp_f32_e32 v73, v73
	v_pk_mul_f32 v[60:61], v[60:61], v[66:67]
	v_pk_mul_f32 v[62:63], v[62:63], v[68:69]
	v_pk_mul_f32 v[56:57], v[56:57], v[70:71]
	v_pk_mul_f32 v[58:59], v[58:59], v[72:73]
	v_pk_mul_f32 v[52:53], v[52:53], v[60:61]
	v_pk_mul_f32 v[54:55], v[54:55], v[62:63]
	v_pk_mul_f32 v[56:57], v[48:49], v[56:57]
	v_pk_mul_f32 v[58:59], v[50:51], v[58:59]
	v_cvt_pk_bf16_f32 v48, v52, v53
	v_cvt_pk_bf16_f32 v49, v54, v55
	v_cvt_pk_bf16_f32 v50, v56, v57
	v_cvt_pk_bf16_f32 v51, v58, v59
	global_store_dwordx4 v[64:65], v[48:51], off
	global_load_dword v48, v[150:151], off offset:576
	s_nop 0
	v_add_u32_e32 v49, 0x90, v144
	s_waitcnt vmcnt(0)
	v_fmamk_f32 v48, v48, 0x3a800000, v158
	v_mul_f32_e32 v50, 0x4b800000, v48
	v_cmp_gt_f32_e32 vcc, s77, v48
	s_nop 1
	v_cndmask_b32_e32 v48, v48, v50, vcc
	v_rsq_f32_e32 v50, v48
	v_mad_i64_i32 v[48:49], s[6:7], v49, s79, v[146:147]
	v_lshl_add_u64 v[48:49], v[48:49], 0, v[148:149]
	v_mul_f32_e32 v51, 0x45800000, v50
	v_cndmask_b32_e32 v50, v50, v51, vcc
	v_pk_mul_f32 v[46:47], v[46:47], v[50:51] op_sel_hi:[1,0]
	v_pk_mul_f32 v[44:45], v[44:45], v[50:51] op_sel_hi:[1,0]
	v_pk_mul_f32 v[42:43], v[42:43], v[50:51] op_sel_hi:[1,0]
	v_pk_mul_f32 v[40:41], v[40:41], v[50:51] op_sel_hi:[1,0]
	v_pk_mul_f32 v[38:39], v[38:39], v[50:51] op_sel_hi:[1,0]
	v_pk_mul_f32 v[36:37], v[36:37], v[50:51] op_sel_hi:[1,0]
	v_pk_mul_f32 v[34:35], v[34:35], v[50:51] op_sel_hi:[1,0]
	v_pk_mul_f32 v[32:33], v[32:33], v[50:51] op_sel_hi:[1,0]
	v_mul_f32_e32 v50, 0xbfb8aa3b, v44
	v_mul_f32_e32 v51, 0xbfb8aa3b, v45
	v_mul_f32_e32 v52, 0xbfb8aa3b, v46
	v_mul_f32_e32 v53, 0xbfb8aa3b, v47
	v_mul_f32_e32 v54, 0xbfb8aa3b, v40
	v_mul_f32_e32 v55, 0xbfb8aa3b, v41
	v_mul_f32_e32 v56, 0xbfb8aa3b, v42
	v_mul_f32_e32 v57, 0xbfb8aa3b, v43
	v_exp_f32_e32 v50, v50
	v_exp_f32_e32 v51, v51
	v_exp_f32_e32 v52, v52
	v_exp_f32_e32 v53, v53
	v_exp_f32_e32 v54, v54
	v_exp_f32_e32 v55, v55
	v_exp_f32_e32 v56, v56
	v_exp_f32_e32 v57, v57
	v_add_f32_e32 v50, 1.0, v50
	v_add_f32_e32 v51, 1.0, v51
	v_add_f32_e32 v52, 1.0, v52
	v_add_f32_e32 v53, 1.0, v53
	v_add_f32_e32 v54, 1.0, v54
	v_add_f32_e32 v55, 1.0, v55
	v_add_f32_e32 v56, 1.0, v56
	v_add_f32_e32 v57, 1.0, v57
	v_rcp_f32_e32 v50, v50
	v_rcp_f32_e32 v51, v51
	v_rcp_f32_e32 v52, v52
	v_rcp_f32_e32 v53, v53
	v_rcp_f32_e32 v54, v54
	v_rcp_f32_e32 v55, v55
	v_rcp_f32_e32 v56, v56
	v_rcp_f32_e32 v57, v57
	v_pk_mul_f32 v[44:45], v[44:45], v[50:51]
	v_pk_mul_f32 v[46:47], v[46:47], v[52:53]
	v_pk_mul_f32 v[40:41], v[40:41], v[54:55]
	v_pk_mul_f32 v[42:43], v[42:43], v[56:57]
	v_pk_mul_f32 v[36:37], v[36:37], v[44:45]
	v_pk_mul_f32 v[38:39], v[38:39], v[46:47]
	v_pk_mul_f32 v[40:41], v[32:33], v[40:41]
	v_pk_mul_f32 v[42:43], v[34:35], v[42:43]
	v_cvt_pk_bf16_f32 v32, v36, v37
	v_cvt_pk_bf16_f32 v33, v38, v39
	v_cvt_pk_bf16_f32 v34, v40, v41
	v_cvt_pk_bf16_f32 v35, v42, v43
	global_store_dwordx4 v[48:49], v[32:35], off
	global_load_dword v32, v[150:151], off offset:640
	s_nop 0
	v_add_u32_e32 v33, 0xa0, v144
	s_waitcnt vmcnt(0)
; __device__ __forceinline__ unsigned cvt_pk_bf16(float lo, float hi) { cvf32x2_t v = {lo, hi}; cvbf16x2_t b = __builtin_convertvector(v, cvbf16x2_t); return __builtin_bit_cast(unsigned, b); }
; #define PG8_BAR __builtin_amdgcn_s_barrier()
; __device__ __forceinline__ float fsilu(float x) { return x * fsigm(x); }
; __device__ __forceinline__ float row_rs(const float* ssq, int row) { return ssq ? rsqrtf(ssq[row] * (1.f / 1024.f) + RMS_EPS) : 1.f; }
; template <class Epi, class Sched, bool ALIGN_EPI = false, bool SP2 = false>
; __device__ __forceinline__ void gemm_phase(PG8_LAS unsigned char* lds, const Gemm g, const Sched& S, const Epi& E) {
;     ...
;         }
;         if constexpr (ALIGN_EPI) { if (wr == 0) PG8_BAR; }
;         if constexpr (!Epi::AFTER_DRAIN) { E(acc, cur, wr, wc, fr, fq); S.done(cur); }
;         if (!has_next) break;
; #pragma unroll
;         for (int a = 0; a < 2; ++a)
; #pragma unroll
;             for (int b = 0; b < 2; ++b)
; #pragma unroll
;                 for (int m = 0; m < 4; ++m)
; #pragma unroll
;                     for (int n = 0; n < 2; ++n) acc[a][b][m][n] = (f32x4){0.f, 0.f, 0.f, 0.f};
;         cur = nxt; cA = nA; cB = nB; ++ui;
;         if constexpr (ALIGN_EPI) { if (wr == 1) PG8_BAR; }
;     }
;     __device__ __forceinline__ void operator()(const f32x4 (&acc)[2][2][4][2], const Unit& u, int wr, int wc, int fr, int fq) const {
;     ...
;             for (int m = 0; m < 4; ++m) { const int row = row0 + ai * HALF + m * 16; const float rs = row_rs(ssq, row);
;                 u32x4 w; unsigned pk[4];
; #pragma unroll
;                 for (int n = 0; n < 2; ++n) { const f32x4 g = acc[ai][0][m][n] * rs, up = acc[ai][1][m][n] * rs;
;                     pk[2 * n] = cvt_pk_bf16(fsilu(g[0]) * up[0], fsilu(g[1]) * up[1]); pk[2 * n + 1] = cvt_pk_bf16(fsilu(g[2]) * up[2], fsilu(g[3]) * up[3]); }
;                 w.x = pk[0]; w.y = pk[1]; w.z = pk[2]; w.w = pk[3];
;                 st_wt16(H + (size_t)row * ldh + col0, w); }
	v_fmamk_f32 v32, v32, 0x3a800000, v158
	v_mul_f32_e32 v34, 0x4b800000, v32
	v_cmp_gt_f32_e32 vcc, s77, v32
	s_nop 1
	v_cndmask_b32_e32 v32, v32, v34, vcc
	v_rsq_f32_e32 v34, v32
	v_mad_i64_i32 v[32:33], s[6:7], v33, s79, v[146:147]
	v_lshl_add_u64 v[32:33], v[32:33], 0, v[148:149]
	v_mul_f32_e32 v35, 0x45800000, v34
	v_cndmask_b32_e32 v34, v34, v35, vcc
	v_pk_mul_f32 v[30:31], v[30:31], v[34:35] op_sel_hi:[1,0]
	v_pk_mul_f32 v[28:29], v[28:29], v[34:35] op_sel_hi:[1,0]
	v_pk_mul_f32 v[26:27], v[26:27], v[34:35] op_sel_hi:[1,0]
	v_pk_mul_f32 v[24:25], v[24:25], v[34:35] op_sel_hi:[1,0]
	v_pk_mul_f32 v[22:23], v[22:23], v[34:35] op_sel_hi:[1,0]
	v_pk_mul_f32 v[20:21], v[20:21], v[34:35] op_sel_hi:[1,0]
	v_pk_mul_f32 v[18:19], v[18:19], v[34:35] op_sel_hi:[1,0]
	v_pk_mul_f32 v[16:17], v[16:17], v[34:35] op_sel_hi:[1,0]
	v_mul_f32_e32 v34, 0xbfb8aa3b, v28
	v_mul_f32_e32 v35, 0xbfb8aa3b, v29
	v_mul_f32_e32 v36, 0xbfb8aa3b, v30
	v_mul_f32_e32 v37, 0xbfb8aa3b, v31
	v_mul_f32_e32 v38, 0xbfb8aa3b, v24
	v_mul_f32_e32 v39, 0xbfb8aa3b, v25
	v_mul_f32_e32 v40, 0xbfb8aa3b, v26
	v_mul_f32_e32 v41, 0xbfb8aa3b, v27
	v_exp_f32_e32 v34, v34
	v_exp_f32_e32 v35, v35
	v_exp_f32_e32 v36, v36
	v_exp_f32_e32 v37, v37
	v_exp_f32_e32 v38, v38
	v_exp_f32_e32 v39, v39
	v_exp_f32_e32 v40, v40
	v_exp_f32_e32 v41, v41
	v_add_f32_e32 v34, 1.0, v34
	v_add_f32_e32 v35, 1.0, v35
	v_add_f32_e32 v36, 1.0, v36
	v_add_f32_e32 v37, 1.0, v37
	v_add_f32_e32 v38, 1.0, v38
	v_add_f32_e32 v39, 1.0, v39
	v_add_f32_e32 v40, 1.0, v40
	v_add_f32_e32 v41, 1.0, v41
	v_rcp_f32_e32 v34, v34
	v_rcp_f32_e32 v35, v35
	v_rcp_f32_e32 v36, v36
	v_rcp_f32_e32 v37, v37
	v_rcp_f32_e32 v38, v38
	v_rcp_f32_e32 v39, v39
	v_rcp_f32_e32 v40, v40
	v_rcp_f32_e32 v41, v41
	v_pk_mul_f32 v[28:29], v[28:29], v[34:35]
	v_pk_mul_f32 v[30:31], v[30:31], v[36:37]
	v_pk_mul_f32 v[24:25], v[24:25], v[38:39]
	v_pk_mul_f32 v[26:27], v[26:27], v[40:41]
	v_pk_mul_f32 v[20:21], v[20:21], v[28:29]
	v_pk_mul_f32 v[22:23], v[22:23], v[30:31]
	v_pk_mul_f32 v[24:25], v[16:17], v[24:25]
	v_pk_mul_f32 v[26:27], v[18:19], v[26:27]
	v_cvt_pk_bf16_f32 v16, v20, v21
	v_cvt_pk_bf16_f32 v17, v22, v23
	v_cvt_pk_bf16_f32 v18, v24, v25
	v_cvt_pk_bf16_f32 v19, v26, v27
	global_store_dwordx4 v[32:33], v[16:19], off
	global_load_dword v16, v[150:151], off offset:704
	s_andn2_b64 vcc, exec, s[4:5]
	v_add_u32_e32 v17, 0xb0, v144
	s_mov_b64 s[4:5], -1
	s_waitcnt vmcnt(0)
	v_fmamk_f32 v16, v16, 0x3a800000, v158
	v_mul_f32_e32 v18, 0x4b800000, v16
	v_cmp_gt_f32_e64 s[6:7], s77, v16
	s_nop 1
	v_cndmask_b32_e64 v16, v16, v18, s[6:7]
	v_rsq_f32_e32 v18, v16
	v_mad_i64_i32 v[16:17], s[34:35], v17, s79, v[146:147]
	v_lshl_add_u64 v[16:17], v[16:17], 0, v[148:149]
	v_mul_f32_e32 v19, 0x45800000, v18
	v_cndmask_b32_e64 v18, v18, v19, s[6:7]
	v_pk_mul_f32 v[14:15], v[14:15], v[18:19] op_sel_hi:[1,0]
	v_pk_mul_f32 v[12:13], v[12:13], v[18:19] op_sel_hi:[1,0]
	v_pk_mul_f32 v[10:11], v[10:11], v[18:19] op_sel_hi:[1,0]
	v_pk_mul_f32 v[8:9], v[8:9], v[18:19] op_sel_hi:[1,0]
	v_pk_mul_f32 v[6:7], v[6:7], v[18:19] op_sel_hi:[1,0]
	v_pk_mul_f32 v[4:5], v[4:5], v[18:19] op_sel_hi:[1,0]
	v_pk_mul_f32 v[2:3], v[2:3], v[18:19] op_sel_hi:[1,0]
	v_pk_mul_f32 v[0:1], v[0:1], v[18:19] op_sel_hi:[1,0]
	v_mul_f32_e32 v18, 0xbfb8aa3b, v12
	v_mul_f32_e32 v19, 0xbfb8aa3b, v13
	v_mul_f32_e32 v20, 0xbfb8aa3b, v14
	v_mul_f32_e32 v21, 0xbfb8aa3b, v15
	v_mul_f32_e32 v22, 0xbfb8aa3b, v8
	v_mul_f32_e32 v23, 0xbfb8aa3b, v9
	v_mul_f32_e32 v24, 0xbfb8aa3b, v10
	v_mul_f32_e32 v25, 0xbfb8aa3b, v11
	v_exp_f32_e32 v18, v18
	v_exp_f32_e32 v19, v19
	v_exp_f32_e32 v20, v20
	v_exp_f32_e32 v21, v21
	v_exp_f32_e32 v22, v22
	v_exp_f32_e32 v23, v23
	v_exp_f32_e32 v24, v24
	v_exp_f32_e32 v25, v25
	v_add_f32_e32 v18, 1.0, v18
	v_add_f32_e32 v19, 1.0, v19
	v_add_f32_e32 v20, 1.0, v20
	v_add_f32_e32 v21, 1.0, v21
	v_add_f32_e32 v22, 1.0, v22
	v_add_f32_e32 v23, 1.0, v23
	v_add_f32_e32 v24, 1.0, v24
	v_add_f32_e32 v25, 1.0, v25
	v_rcp_f32_e32 v18, v18
	v_rcp_f32_e32 v19, v19
	v_rcp_f32_e32 v20, v20
	v_rcp_f32_e32 v21, v21
	v_rcp_f32_e32 v22, v22
	v_rcp_f32_e32 v23, v23
	v_rcp_f32_e32 v24, v24
	v_rcp_f32_e32 v25, v25
	v_pk_mul_f32 v[12:13], v[12:13], v[18:19]
	v_pk_mul_f32 v[14:15], v[14:15], v[20:21]
	v_pk_mul_f32 v[8:9], v[8:9], v[22:23]
	v_pk_mul_f32 v[10:11], v[10:11], v[24:25]
	v_pk_mul_f32 v[4:5], v[4:5], v[12:13]
	v_pk_mul_f32 v[6:7], v[6:7], v[14:15]
	v_pk_mul_f32 v[8:9], v[0:1], v[8:9]
	v_pk_mul_f32 v[10:11], v[2:3], v[10:11]
	v_cvt_pk_bf16_f32 v0, v4, v5
	v_cvt_pk_bf16_f32 v1, v6, v7
	v_cvt_pk_bf16_f32 v2, v8, v9
	v_cvt_pk_bf16_f32 v3, v10, v11
	global_store_dwordx4 v[16:17], v[0:3], off
	s_cbranch_vccnz .LBB0_1267
	s_andn2_b64 vcc, exec, s[10:11]
	s_cbranch_vccnz .LBB0_1266
	s_barrier
	s_branch .LBB0_1266
